# all individually validated neutral-or-better edits together (attention trims, sink prefetch, hfold loads, LRU barrier removals, gemm_tile prologue wait, no-op fmac removal, h0-row load hoist) on top o
# speedup vs baseline: 1.0098x; 1.0036x over previous
; DEVI unsigned pk2(float lo, float hi) { f32x2 v = {lo, hi}; bf16x2_t b = __builtin_convertvector(v, bf16x2_t); return __builtin_bit_cast(unsigned, b); }
; DEVI float bflo(unsigned u) { return __uint_as_float(u << 16); }
; DEVI float bfhi(unsigned u) { return __uint_as_float(u & 0xffff0000u); }
; template <bool PASS_C>
; DEVI void lru_item(const P& p, int item, int next_item, uint4& u0, uint4& u1, uint4& u2, float& cpre, char* smem) {
;     ...
;     {
;         const int tok = tid >> 2, cg0 = (tid & 3) * 16;
;         uint4 r[4][2];
; #pragma unroll
;         for (int k = 0; k < 4; ++k) { r[k][0] = *(const uint4*)(us + (tok + k) * 64 + cg0); r[k][1] = *(const uint4*)(us + (tok + k) * 64 + cg0 + 8); }
;         float val[16];
; #pragma unroll
;         for (int e = 0; e < 16; ++e) {
;             const int ch = cg0 + e;
;             float a = prm[4 * 64 + ch];
; #pragma unroll
;             for (int k = 0; k < 4; ++k) {
;                 const uint4 q = r[k][e >> 3];
;                 const unsigned wd = ((e >> 1) & 3) == 0 ? q.x : (((e >> 1) & 3) == 1 ? q.y : (((e >> 1) & 3) == 2 ? q.z : q.w));
;                 a += prm[k * 64 + ch] * ((e & 1) ? bfhi(wd) : bflo(wd));
;             }
;             val[e] = a;
;         }
;         uint4 o;
;         o.x = pk2(val[0], val[1]); o.y = pk2(val[2], val[3]); o.z = pk2(val[4], val[5]); o.w = pk2(val[6], val[7]);
;         *(uint4*)(ucb + tok * 128 + ((((cg0 >> 3) + 0) ^ (tok & 7)) << 4)) = o;
;         o.x = pk2(val[8], val[9]); o.y = pk2(val[10], val[11]); o.z = pk2(val[12], val[13]); o.w = pk2(val[14], val[15]);
;         *(uint4*)(ucb + tok * 128 + ((((cg0 >> 3) + 1) ^ (tok & 7)) << 4)) = o;
;     }
.LBB0_510:
	s_waitcnt lgkmcnt(0)
	s_barrier
	ds_read_b128 v[32:35], v118 offset:35840
	ds_read_b128 v[12:15], v118 offset:35856
	ds_read_b128 v[36:39], v118 offset:35968
	ds_read_b128 v[16:19], v118 offset:35984
	ds_read_b128 v[40:43], v118 offset:36096
	ds_read_b128 v[20:23], v118 offset:36112
	ds_read_b128 v[44:47], v118 offset:36224
	ds_read_b128 v[24:27], v118 offset:36240
	ds_read_b128 v[48:51], v111 offset:33792
	ds_read_b128 v[52:55], v111 offset:32768
	ds_read_b128 v[56:59], v111 offset:32784
	ds_read_b128 v[60:63], v111 offset:32800
	ds_read_b128 v[28:31], v111 offset:32816
	ds_read_b128 v[64:67], v111 offset:33024
	ds_read_b128 v[92:95], v111 offset:33808
	s_waitcnt lgkmcnt(14)
	v_lshlrev_b32_e32 v96, 16, v32
	v_and_b32_e32 v97, 0xffff0000, v32
	s_waitcnt lgkmcnt(5)
	v_pk_fma_f32 v[48:49], v[52:53], v[96:97], v[48:49]
	ds_read_b128 v[96:99], v111 offset:33280
	ds_read_b128 v[146:149], v111 offset:33536
	ds_read_b128 v[150:153], v111 offset:33040
	v_lshlrev_b32_e32 v32, 16, v33
	v_and_b32_e32 v33, 0xffff0000, v33
	v_lshlrev_b32_e32 v154, 16, v36
	v_and_b32_e32 v155, 0xffff0000, v36
	v_lshlrev_b32_e32 v36, 16, v37
	v_and_b32_e32 v37, 0xffff0000, v37
	v_pk_fma_f32 v[32:33], v[54:55], v[32:33], v[50:51]
	v_lshlrev_b32_e32 v158, 16, v40
	v_and_b32_e32 v159, 0xffff0000, v40
	s_waitcnt lgkmcnt(4)
	v_pk_fma_f32 v[48:49], v[64:65], v[154:155], v[48:49]
	ds_read_b128 v[154:157], v111 offset:33296
	v_lshlrev_b32_e32 v40, 16, v41
	v_and_b32_e32 v41, 0xffff0000, v41
	v_pk_fma_f32 v[32:33], v[66:67], v[36:37], v[32:33]
	v_lshlrev_b32_e32 v162, 16, v44
	v_and_b32_e32 v163, 0xffff0000, v44
	s_waitcnt lgkmcnt(3)
	v_pk_fma_f32 v[48:49], v[96:97], v[158:159], v[48:49]
	ds_read_b128 v[158:161], v111 offset:33552
	v_lshlrev_b32_e32 v44, 16, v45
	v_and_b32_e32 v45, 0xffff0000, v45
	v_pk_fma_f32 v[32:33], v[98:99], v[40:41], v[32:33]
	v_lshlrev_b32_e32 v36, 16, v38
	s_waitcnt lgkmcnt(3)
	v_pk_fma_f32 v[98:99], v[148:149], v[44:45], v[32:33]
	v_lshlrev_b32_e32 v32, 16, v34
	v_and_b32_e32 v33, 0xffff0000, v34
	v_and_b32_e32 v37, 0xffff0000, v38
	v_pk_fma_f32 v[32:33], v[56:57], v[32:33], v[92:93]
	v_lshlrev_b32_e32 v40, 16, v42
	v_and_b32_e32 v41, 0xffff0000, v42
	s_waitcnt lgkmcnt(2)
	v_pk_fma_f32 v[32:33], v[150:151], v[36:37], v[32:33]
	v_lshlrev_b32_e32 v44, 16, v46
	v_and_b32_e32 v45, 0xffff0000, v46
	s_waitcnt lgkmcnt(1)
	v_pk_fma_f32 v[32:33], v[154:155], v[40:41], v[32:33]
	v_lshlrev_b32_e32 v34, 16, v39
	s_waitcnt lgkmcnt(0)
	v_pk_fma_f32 v[92:93], v[158:159], v[44:45], v[32:33]
	v_lshlrev_b32_e32 v32, 16, v35
	v_and_b32_e32 v33, 0xffff0000, v35
	v_and_b32_e32 v35, 0xffff0000, v39
	v_pk_fma_f32 v[32:33], v[58:59], v[32:33], v[94:95]
	v_lshlrev_b32_e32 v36, 16, v43
	v_and_b32_e32 v37, 0xffff0000, v43
	v_pk_fma_f32 v[32:33], v[152:153], v[34:35], v[32:33]
	v_lshlrev_b32_e32 v38, 16, v47
	v_and_b32_e32 v39, 0xffff0000, v47
	v_pk_fma_f32 v[32:33], v[156:157], v[36:37], v[32:33]
	v_lshlrev_b32_e32 v44, 16, v12
	v_pk_fma_f32 v[94:95], v[160:161], v[38:39], v[32:33]
	ds_read_b128 v[32:35], v111 offset:33824
	ds_read_b128 v[36:39], v111 offset:33056
	ds_read_b128 v[40:43], v111 offset:33840
	v_and_b32_e32 v45, 0xffff0000, v12
	v_pk_fma_f32 v[96:97], v[146:147], v[162:163], v[48:49]
	v_lshlrev_b32_e32 v12, 16, v13
	s_waitcnt lgkmcnt(2)
	v_pk_fma_f32 v[32:33], v[60:61], v[44:45], v[32:33]
	ds_read_b128 v[44:47], v111 offset:33312
	ds_read_b128 v[48:51], v111 offset:33568
	ds_read_b128 v[52:55], v111 offset:33072
	v_and_b32_e32 v13, 0xffff0000, v13
	v_lshlrev_b32_e32 v56, 16, v16
	v_and_b32_e32 v57, 0xffff0000, v16
	v_lshlrev_b32_e32 v16, 16, v17
	v_and_b32_e32 v17, 0xffff0000, v17
	v_pk_fma_f32 v[12:13], v[62:63], v[12:13], v[34:35]
	v_lshlrev_b32_e32 v64, 16, v20
	v_and_b32_e32 v65, 0xffff0000, v20
	s_waitcnt lgkmcnt(4)
	v_pk_fma_f32 v[32:33], v[36:37], v[56:57], v[32:33]
	ds_read_b128 v[56:59], v111 offset:33328
	v_lshlrev_b32_e32 v20, 16, v21
	v_and_b32_e32 v21, 0xffff0000, v21
	v_pk_fma_f32 v[12:13], v[38:39], v[16:17], v[12:13]
	v_lshlrev_b32_e32 v146, 16, v24
	v_and_b32_e32 v147, 0xffff0000, v24
	s_waitcnt lgkmcnt(3)
	v_pk_fma_f32 v[32:33], v[44:45], v[64:65], v[32:33]
	ds_read_b128 v[64:67], v111 offset:33584
	v_lshlrev_b32_e32 v24, 16, v25
	v_and_b32_e32 v25, 0xffff0000, v25
	v_pk_fma_f32 v[12:13], v[46:47], v[20:21], v[12:13]
	v_lshlrev_b32_e32 v20, 16, v18
	s_waitcnt lgkmcnt(3)
	v_pk_fma_f32 v[16:17], v[50:51], v[24:25], v[12:13]
	v_lshlrev_b32_e32 v12, 16, v14
	v_and_b32_e32 v13, 0xffff0000, v14
	v_and_b32_e32 v21, 0xffff0000, v18
	v_pk_fma_f32 v[12:13], v[28:29], v[12:13], v[40:41]
	v_lshlrev_b32_e32 v24, 16, v22
	v_and_b32_e32 v25, 0xffff0000, v22
	s_waitcnt lgkmcnt(2)
	v_pk_fma_f32 v[12:13], v[52:53], v[20:21], v[12:13]
	v_lshlrev_b32_e32 v34, 16, v26
	v_and_b32_e32 v35, 0xffff0000, v26
	s_waitcnt lgkmcnt(1)
	v_pk_fma_f32 v[12:13], v[56:57], v[24:25], v[12:13]
	v_lshlrev_b32_e32 v14, 16, v19
	s_waitcnt lgkmcnt(0)
	v_pk_fma_f32 v[20:21], v[64:65], v[34:35], v[12:13]
	v_lshlrev_b32_e32 v12, 16, v15
	v_and_b32_e32 v13, 0xffff0000, v15
	v_and_b32_e32 v15, 0xffff0000, v19
	v_pk_fma_f32 v[12:13], v[30:31], v[12:13], v[42:43]
	v_lshlrev_b32_e32 v18, 16, v23
	v_and_b32_e32 v19, 0xffff0000, v23
	v_pk_fma_f32 v[12:13], v[54:55], v[14:15], v[12:13]
	v_lshlrev_b32_e32 v22, 16, v27
	v_and_b32_e32 v23, 0xffff0000, v27
	v_pk_fma_f32 v[12:13], v[58:59], v[18:19], v[12:13]
	v_pk_fma_f32 v[32:33], v[48:49], v[146:147], v[32:33]
	v_pk_fma_f32 v[18:19], v[66:67], v[22:23], v[12:13]
	v_cvt_pk_bf16_f32 v12, v96, v97
	v_cvt_pk_bf16_f32 v13, v98, v99
	v_cvt_pk_bf16_f32 v14, v92, v93
	v_cvt_pk_bf16_f32 v15, v94, v95
	ds_write_b128 v119, v[12:15] offset:44544
	v_cvt_pk_bf16_f32 v12, v32, v33
	v_cvt_pk_bf16_f32 v13, v16, v17
	v_cvt_pk_bf16_f32 v14, v20, v21
	v_cvt_pk_bf16_f32 v15, v18, v19
	ds_write_b128 v120, v[12:15] offset:44544
	v_add_u32_e32 v12, v113, v114
	s_waitcnt lgkmcnt(0)
; template <bool PASS_C>
; DEVI void lru_item(const P& p, int item, int next_item, uint4& u0, uint4& u1, uint4& u2, float& cpre, char* smem) {
;     ...
;     f32x4 acc[16];
; #pragma unroll
;     for (int n = 0; n < 16; ++n) acc[n] = (f32x4){0.f, 0.f, 0.f, 0.f};
;     {
;         bf16x8 af[2];
; #pragma unroll
;         for (int kk = 0; kk < 2; ++kk) af[kk] = *(const bf16x8*)(ucb + (16 * w + fr) * 128 + (((kk * 4 + fq) ^ (fr & 7)) << 4));
; #pragma unroll
;         for (int n = 0; n < 16; ++n)
; #pragma unroll
;             for (int kk = 0; kk < 2; ++kk) {
;                 const bf16x8 bfr = *(const bf16x8*)(smem + (16 * n + fr) * 128 + (((kk * 4 + fq) ^ (fr & 7)) << 4));
;                 acc[n] = __builtin_amdgcn_mfma_f32_16x16x32_bf16(af[kk], bfr, acc[n], 0, 0, 0);
;             }
;     }
	v_add_u32_e32 v75, v112, v114
	v_add_u32_e32 v20, v113, v115
	v_add_u32_e32 v77, v112, v115
	ds_read_b128 v[12:15], v12 offset:44544
	ds_read_b128 v[92:95], v20 offset:44544
	ds_read_b32 v83, v116 offset:35072
	ds_read_b128 v[232:235], v75
	ds_read_b128 v[236:239], v77
	ds_read_b128 v[240:243], v75 offset:2048
	ds_read_b128 v[244:247], v77 offset:2048
	ds_read_b128 v[248:251], v75 offset:4096
	ds_read_b128 v[158:161], v77 offset:4096
	ds_read_b128 v[252:255], v75 offset:6144
	ds_read_b128 v[218:221], v77 offset:6144
	s_waitcnt lgkmcnt(4)
	v_mfma_f32_16x16x32_bf16 v[146:149], v[12:15], v[232:235], 0
	ds_read_b128 v[222:225], v75 offset:8192
	ds_read_b128 v[226:229], v77 offset:8192
	ds_read_b128 v[96:99], v75 offset:10240
	ds_read_b128 v[154:157], v77 offset:10240
	v_mfma_f32_16x16x32_bf16 v[56:59], v[12:15], v[240:243], 0
	v_mfma_f32_16x16x32_bf16 v[146:149], v[92:95], v[236:239], v[146:149]
	v_mfma_f32_16x16x32_bf16 v[56:59], v[92:95], v[244:247], v[56:59]
	s_waitcnt lgkmcnt(4)
	v_mfma_f32_16x16x32_bf16 v[40:43], v[12:15], v[248:251], 0
	ds_read_b128 v[232:235], v75 offset:12288
	ds_read_b128 v[236:239], v77 offset:12288
	ds_read_b128 v[240:243], v75 offset:14336
	ds_read_b128 v[244:247], v77 offset:14336
	v_mfma_f32_16x16x32_bf16 v[24:27], v[12:15], v[252:255], 0
	v_mfma_f32_16x16x32_bf16 v[40:43], v[92:95], v[158:161], v[40:43]
	v_mfma_f32_16x16x32_bf16 v[24:27], v[92:95], v[218:221], v[24:27]
	s_waitcnt lgkmcnt(4)
	v_mfma_f32_16x16x32_bf16 v[150:153], v[12:15], v[222:225], 0
	ds_read_b128 v[248:251], v75 offset:16384
	ds_read_b128 v[158:161], v77 offset:16384
	ds_read_b128 v[252:255], v75 offset:18432
	ds_read_b128 v[218:221], v77 offset:18432
	v_mfma_f32_16x16x32_bf16 v[52:55], v[12:15], v[96:99], 0
	v_mfma_f32_16x16x32_bf16 v[150:153], v[92:95], v[226:229], v[150:153]
	v_mfma_f32_16x16x32_bf16 v[52:55], v[92:95], v[154:157], v[52:55]
	s_waitcnt lgkmcnt(4)
	v_mfma_f32_16x16x32_bf16 v[36:39], v[12:15], v[232:235], 0
	ds_read_b128 v[222:225], v75 offset:20480
	ds_read_b128 v[226:229], v77 offset:20480
	ds_read_b128 v[96:99], v75 offset:22528
	ds_read_b128 v[154:157], v77 offset:22528
	v_mfma_f32_16x16x32_bf16 v[20:23], v[12:15], v[240:243], 0
	v_mfma_f32_16x16x32_bf16 v[36:39], v[92:95], v[236:239], v[36:39]
	v_mfma_f32_16x16x32_bf16 v[20:23], v[92:95], v[244:247], v[20:23]
	s_waitcnt lgkmcnt(4)
	v_mfma_f32_16x16x32_bf16 v[64:67], v[12:15], v[248:251], 0
	ds_read_b128 v[232:235], v75 offset:24576
	ds_read_b128 v[236:239], v77 offset:24576
	ds_read_b128 v[240:243], v75 offset:26624
	ds_read_b128 v[244:247], v77 offset:26624
	v_mfma_f32_16x16x32_bf16 v[48:51], v[12:15], v[252:255], 0
	v_mfma_f32_16x16x32_bf16 v[64:67], v[92:95], v[158:161], v[64:67]
	v_mfma_f32_16x16x32_bf16 v[48:51], v[92:95], v[218:221], v[48:51]
	s_waitcnt lgkmcnt(4)
	v_mfma_f32_16x16x32_bf16 v[32:35], v[12:15], v[222:225], 0
	ds_read_b128 v[248:251], v75 offset:28672
	ds_read_b128 v[252:255], v75 offset:30720
	ds_read_b128 v[158:161], v77 offset:28672
	v_mfma_f32_16x16x32_bf16 v[16:19], v[12:15], v[96:99], 0
	v_mfma_f32_16x16x32_bf16 v[32:35], v[92:95], v[226:229], v[32:35]
	v_mfma_f32_16x16x32_bf16 v[16:19], v[92:95], v[154:157], v[16:19]
	s_waitcnt lgkmcnt(3)
	v_mfma_f32_16x16x32_bf16 v[60:63], v[12:15], v[232:235], 0
	v_mfma_f32_16x16x32_bf16 v[44:47], v[12:15], v[240:243], 0
	v_mfma_f32_16x16x32_bf16 v[60:63], v[92:95], v[236:239], v[60:63]
	v_mfma_f32_16x16x32_bf16 v[44:47], v[92:95], v[244:247], v[44:47]
	s_waitcnt lgkmcnt(1)
; template <bool PASS_C>
; DEVI void lru_item(const P& p, int item, int next_item, uint4& u0, uint4& u1, uint4& u2, float& cpre, char* smem) {
;     ...
;         for (int kk = 0; kk < 2; ++kk) af[kk] = *(const bf16x8*)(ucb + (16 * w + fr) * 128 + (((kk * 4 + fq) ^ (fr & 7)) << 4));
; #pragma unroll
;         for (int n = 0; n < 16; ++n)
; #pragma unroll
;             for (int kk = 0; kk < 2; ++kk) {
;                 const bf16x8 bfr = *(const bf16x8*)(smem + (16 * n + fr) * 128 + (((kk * 4 + fq) ^ (fr & 7)) << 4));
;                 acc[n] = __builtin_amdgcn_mfma_f32_16x16x32_bf16(af[kk], bfr, acc[n], 0, 0, 0);
;             }
;     }
;     float av[4][2][4], bv[4][2][4], apre[4][2], bpre[4][2];
; #pragma unroll
;     for (int nn = 0; nn < 4; ++nn) {
;         const int ch = 16 * nn + fr;
;         float uc[4];
; #pragma unroll
;         for (int j = 0; j < 4; ++j) {
;             const int tl = 16 * w + 4 * fq + j;
;             uc[j] = bf2f(*(const bf16_t*)(ucb + tl * 128 + ((((ch >> 3)) ^ (tl & 7)) << 4) + (ch & 7) * 2));
;         }
; #pragma unroll
;         for (int d = 0; d < 2; ++d) {
;             const float ba = prm[(5 + d) * 64 + ch], bx = prm[(7 + d) * 64 + ch], nsp8 = prm[(9 + d) * 64 + ch];
; #pragma unroll
;             for (int j = 0; j < 4; ++j) {
;                 const float r = __builtin_amdgcn_rcpf(1.0f + __builtin_amdgcn_exp2f(__builtin_fmaf(acc[(2 * d) * 4 + nn][j], -LOG2E, ba)));
;                 const float ig = __builtin_amdgcn_rcpf(1.0f + __builtin_amdgcn_exp2f(__builtin_fmaf(acc[(2 * d + 1) * 4 + nn][j], -LOG2E, bx)));
;                 const float a_ = __builtin_amdgcn_exp2f(nsp8 * r);
;                 av[nn][d][j] = a_;
;                 bv[nn][d][j] = __builtin_amdgcn_sqrtf(__builtin_fmaf(-a_, a_, 1.0f)) * ig * uc[j];
;             }
;             float A = 1.f, Bq = 0.f;
;             if (d == 0) {
; #pragma unroll
;                 for (int j = 0; j < 4; ++j) { Bq = av[nn][d][j] * Bq + bv[nn][d][j]; A *= av[nn][d][j]; }
;             } else {
; #pragma unroll
;                 for (int j = 3; j >= 0; --j) { Bq = av[nn][d][j] * Bq + bv[nn][d][j]; A *= av[nn][d][j]; }
;             }
;             float Ag[4], Bg[4];
;             rowgather4(A, Ag); rowgather4(Bq, Bg);
;             float AW = 1.f, BW = 0.f, AP = 1.f, BP = 0.f;
;             if (d == 0) {
; #pragma unroll
;                 for (int g = 0; g < 4; ++g) {
	v_mfma_f32_16x16x32_bf16 v[28:31], v[12:15], v[248:251], 0
	v_mfma_f32_16x16x32_bf16 v[12:15], v[12:15], v[252:255], 0
	ds_read_b128 v[96:99], v77 offset:30720
	ds_read2st64_b32 v[154:155], v116 offset0:133 offset1:135
	ds_read_u16 v246, v121 offset:44544
	ds_read_u16 v247, v122 offset:44544
	ds_read_u16 v248, v123 offset:44544
	ds_read_u16 v249, v124 offset:44544
	ds_read2st64_b32 v[232:233], v116 offset0:134 offset1:136
	ds_read_b32 v250, v116 offset:35328
	v_add_u32_e32 v217, 64, v116
	ds_read2st64_b32 v[234:235], v217 offset0:133 offset1:135
	ds_read_u16 v251, v125 offset:44544
	ds_read_u16 v252, v126 offset:44544
	ds_read_u16 v253, v127 offset:44544
	ds_read_u16 v254, v128 offset:44544
	ds_read_b32 v255, v116 offset:35136
	v_add_u32_e32 v217, 64, v116
	ds_read2st64_b32 v[236:237], v217 offset0:134 offset1:136
	ds_read_b32 v218, v116 offset:35392
	v_add_u32_e32 v217, 0x80, v116
	ds_read2st64_b32 v[238:239], v217 offset0:133 offset1:135
	ds_read_u16 v219, v129 offset:44544
	ds_read_u16 v220, v130 offset:44544
	ds_read_u16 v221, v131 offset:44544
	ds_read_u16 v222, v132 offset:44544
	ds_read_b32 v223, v116 offset:35200
	v_add_u32_e32 v217, 0x80, v116
	ds_read2st64_b32 v[240:241], v217 offset0:134 offset1:136
	ds_read_b32 v224, v116 offset:35456
	v_add_u32_e32 v217, 0xc0, v116
	ds_read2st64_b32 v[242:243], v217 offset0:133 offset1:135
	ds_read_u16 v225, v133 offset:44544
	ds_read_u16 v226, v134 offset:44544
	ds_read_u16 v227, v135 offset:44544
	ds_read_u16 v228, v136 offset:44544
	ds_read_b32 v229, v116 offset:35264
	v_add_u32_e32 v217, 0xc0, v116
	ds_read2st64_b32 v[244:245], v217 offset0:134 offset1:136
	ds_read_b32 v231, v116 offset:35520
	s_waitcnt lgkmcnt(0)
	v_fmamk_f32 v81, v146, 0xbfb8aa3b, v154
	v_exp_f32_e32 v81, v81
	v_fmamk_f32 v91, v149, 0xbfb8aa3b, v154
	v_exp_f32_e32 v91, v91
	v_mfma_f32_16x16x32_bf16 v[28:31], v[92:95], v[158:161], v[28:31]
	v_add_f32_e32 v81, 1.0, v81
	v_rcp_f32_e32 v87, v81
	v_fmamk_f32 v81, v147, 0xbfb8aa3b, v154
	v_exp_f32_e32 v89, v81
	v_lshlrev_b32_e32 v81, 16, v249
	v_mul_f32_e32 v85, v83, v87
	v_mfma_f32_16x16x32_bf16 v[12:15], v[92:95], v[96:99], v[12:15]
	v_add_f32_e32 v87, 1.0, v89
	v_fmamk_f32 v89, v148, 0xbfb8aa3b, v154
	v_exp_f32_e32 v89, v89
	v_add_f32_e32 v91, 1.0, v91
	v_fmamk_f32 v93, v150, 0xbfb8aa3b, v155
	v_rcp_f32_e32 v87, v87
	v_add_f32_e32 v89, 1.0, v89
	v_exp_f32_e32 v85, v85
	v_rcp_f32_e32 v89, v89
	v_rcp_f32_e32 v91, v91
	v_exp_f32_e32 v93, v93
	v_mul_f32_e32 v87, v83, v87
	v_mul_f32_e32 v89, v83, v89
	v_mul_f32_e32 v83, v83, v91
	v_add_f32_e32 v91, 1.0, v93
	v_fma_f32 v93, -v85, v85, 1.0
	v_rcp_f32_e32 v91, v91
	v_sqrt_f32_e32 v93, v93
	v_fmamk_f32 v94, v151, 0xbfb8aa3b, v155
	v_exp_f32_e32 v87, v87
	v_exp_f32_e32 v94, v94
	v_lshlrev_b32_e32 v75, 16, v246
	v_mul_f32_e32 v91, v91, v93
	v_mul_f32_e32 v91, v91, v75
	v_mul_f32_e32 v92, v85, v87
	v_add_f32_e32 v85, 1.0, v94
	v_fma_f32 v93, -v87, v87, 1.0
	v_rcp_f32_e32 v85, v85
	v_sqrt_f32_e32 v93, v93
	v_mul_f32_e32 v87, v87, v91
	v_fmamk_f32 v91, v152, 0xbfb8aa3b, v155
	v_exp_f32_e32 v89, v89
	v_exp_f32_e32 v91, v91
	v_lshlrev_b32_e32 v77, 16, v247
	v_mul_f32_e32 v85, v85, v93
	v_fmac_f32_e32 v87, v85, v77
	v_fmamk_f32 v155, v153, 0xbfb8aa3b, v155
	v_exp_f32_e32 v83, v83
	v_mul_f32_e32 v85, v89, v87
	v_add_f32_e32 v87, 1.0, v91
	v_exp_f32_e32 v91, v155
	v_mul_f32_e32 v92, v89, v92
	v_fma_f32 v89, -v89, v89, 1.0
	v_rcp_f32_e32 v87, v87
	v_sqrt_f32_e32 v89, v89
	v_add_f32_e32 v91, 1.0, v91
	v_fma_f32 v93, -v83, v83, 1.0
	v_rcp_f32_e32 v91, v91
	v_sqrt_f32_e32 v93, v93
	v_lshlrev_b32_e32 v79, 16, v248
	v_mul_f32_e32 v87, v87, v89
	v_fmac_f32_e32 v85, v87, v79
	v_mul_f32_e32 v92, v83, v92
	v_mul_f32_e32 v83, v83, v85
	v_mul_f32_e32 v85, v91, v93
	v_fmac_f32_e32 v83, v85, v81
	v_mov_b32_e32 v96, v92
	v_mov_b32_e32 v85, v83
	s_nop 0
	v_permlane16_swap_b32_e32 v92, v96
	v_permlane16_swap_b32_e32 v83, v85
	v_mov_b32_e32 v94, v92
	v_mov_b32_e32 v95, v96
	v_mov_b32_e32 v97, v83
	v_mov_b32_e32 v99, v85
	v_permlane32_swap_b32_e32 v92, v94
	v_permlane32_swap_b32_e32 v96, v95
	v_permlane32_swap_b32_e32 v83, v97
	v_permlane32_swap_b32_e32 v85, v99
	s_and_saveexec_b64 s[12:13], s[8:9]
	s_cbranch_execz .LBB0_512
	v_fmac_f32_e32 v85, v83, v96
	v_mul_f32_e32 v93, v85, v94
	v_pk_mul_f32 v[146:147], v[92:93], v[96:97]
	v_pk_add_f32 v[92:93], v[92:93], v[96:97]
	v_mov_b32_e32 v96, v95
	v_mov_b32_e32 v92, v146
	v_mov_b32_e32 v98, v95
	v_pk_mul_f32 v[146:147], v[146:147], v[94:95]
	v_pk_fma_f32 v[92:93], v[92:93], v[94:95], v[98:99]
	v_pk_mul_f32 v[96:97], v[146:147], v[96:97]
	s_nop 0
	v_mov_b32_e32 v97, v93
	ds_write_b64 v141, v[96:97] offset:52736

; DEVI unsigned pk2(float lo, float hi) { f32x2 v = {lo, hi}; bf16x2_t b = __builtin_convertvector(v, bf16x2_t); return __builtin_bit_cast(unsigned, b); }
; DEVI float bflo(unsigned u) { return __uint_as_float(u << 16); }
; DEVI float bfhi(unsigned u) { return __uint_as_float(u & 0xffff0000u); }
; template <bool PASS_C>
; DEVI void lru_item(const P& p, int item, int next_item, uint4& u0, uint4& u1, uint4& u2, float& cpre, char* smem) {
;     ...
;     {
;         const int tok = tid >> 2, cg0 = (tid & 3) * 16;
;         uint4 r[4][2];
; #pragma unroll
;         for (int k = 0; k < 4; ++k) { r[k][0] = *(const uint4*)(us + (tok + k) * 64 + cg0); r[k][1] = *(const uint4*)(us + (tok + k) * 64 + cg0 + 8); }
;         float val[16];
; #pragma unroll
;         for (int e = 0; e < 16; ++e) {
;             const int ch = cg0 + e;
;             float a = prm[4 * 64 + ch];
; #pragma unroll
;             for (int k = 0; k < 4; ++k) {
;                 const uint4 q = r[k][e >> 3];
;                 const unsigned wd = ((e >> 1) & 3) == 0 ? q.x : (((e >> 1) & 3) == 1 ? q.y : (((e >> 1) & 3) == 2 ? q.z : q.w));
;                 a += prm[k * 64 + ch] * ((e & 1) ? bfhi(wd) : bflo(wd));
;             }
;             val[e] = a;
;         }
;         uint4 o;
;         o.x = pk2(val[0], val[1]); o.y = pk2(val[2], val[3]); o.z = pk2(val[4], val[5]); o.w = pk2(val[6], val[7]);
;         *(uint4*)(ucb + tok * 128 + ((((cg0 >> 3) + 0) ^ (tok & 7)) << 4)) = o;
;         o.x = pk2(val[8], val[9]); o.y = pk2(val[10], val[11]); o.z = pk2(val[12], val[13]); o.w = pk2(val[14], val[15]);
;         *(uint4*)(ucb + tok * 128 + ((((cg0 >> 3) + 1) ^ (tok & 7)) << 4)) = o;
;     }
.LBB0_739:
	v_lshlrev_b64 v[106:107], 10, v[22:23]
	s_waitcnt lgkmcnt(0)
	s_barrier
	ds_read_b128 v[42:45], v127 offset:35840
	ds_read_b128 v[22:25], v127 offset:35856
	ds_read_b128 v[46:49], v127 offset:35968
	ds_read_b128 v[26:29], v127 offset:35984
	ds_read_b128 v[50:53], v127 offset:36096
	ds_read_b128 v[30:33], v127 offset:36112
	ds_read_b128 v[54:57], v127 offset:36224
	ds_read_b128 v[34:37], v127 offset:36240
	ds_read_b128 v[58:61], v117 offset:33792
	ds_read_b128 v[62:65], v117 offset:32768
	ds_read_b128 v[66:69], v117 offset:32784
	ds_read_b128 v[70:73], v117 offset:32800
	ds_read_b128 v[38:41], v117 offset:32816
	ds_read_b128 v[74:77], v117 offset:33024
	ds_read_b128 v[158:161], v117 offset:33808
	s_waitcnt lgkmcnt(14)
	v_lshlrev_b32_e32 v162, 16, v42
	v_and_b32_e32 v163, 0xffff0000, v42
	s_waitcnt lgkmcnt(5)
	v_pk_fma_f32 v[58:59], v[62:63], v[162:163], v[58:59]
	ds_read_b128 v[162:165], v117 offset:33280
	ds_read_b128 v[166:169], v117 offset:33536
	ds_read_b128 v[184:187], v117 offset:33040
	v_lshlrev_b32_e32 v42, 16, v43
	v_and_b32_e32 v43, 0xffff0000, v43
	v_lshlrev_b32_e32 v170, 16, v46
	v_and_b32_e32 v171, 0xffff0000, v46
	v_lshlrev_b32_e32 v46, 16, v47
	v_and_b32_e32 v47, 0xffff0000, v47
	v_pk_fma_f32 v[42:43], v[64:65], v[42:43], v[60:61]
	v_lshlrev_b32_e32 v192, 16, v50
	v_and_b32_e32 v193, 0xffff0000, v50
	s_waitcnt lgkmcnt(4)
	v_pk_fma_f32 v[58:59], v[74:75], v[170:171], v[58:59]
	ds_read_b128 v[188:191], v117 offset:33296
	v_lshlrev_b32_e32 v50, 16, v51
	v_and_b32_e32 v51, 0xffff0000, v51
	v_pk_fma_f32 v[42:43], v[76:77], v[46:47], v[42:43]
	v_lshlrev_b32_e32 v196, 16, v54
	v_and_b32_e32 v197, 0xffff0000, v54
	s_waitcnt lgkmcnt(3)
	v_pk_fma_f32 v[58:59], v[162:163], v[192:193], v[58:59]
	ds_read_b128 v[192:195], v117 offset:33552
	v_lshlrev_b32_e32 v54, 16, v55
	v_and_b32_e32 v55, 0xffff0000, v55
	v_pk_fma_f32 v[42:43], v[164:165], v[50:51], v[42:43]
	v_lshlrev_b32_e32 v46, 16, v48
	s_waitcnt lgkmcnt(3)
	v_pk_fma_f32 v[164:165], v[168:169], v[54:55], v[42:43]
	v_lshlrev_b32_e32 v42, 16, v44
	v_and_b32_e32 v43, 0xffff0000, v44
	v_and_b32_e32 v47, 0xffff0000, v48
	v_pk_fma_f32 v[42:43], v[66:67], v[42:43], v[158:159]
	v_lshlrev_b32_e32 v50, 16, v52
	v_and_b32_e32 v51, 0xffff0000, v52
	s_waitcnt lgkmcnt(2)
	v_pk_fma_f32 v[42:43], v[184:185], v[46:47], v[42:43]
	v_lshlrev_b32_e32 v54, 16, v56
	v_and_b32_e32 v55, 0xffff0000, v56
	s_waitcnt lgkmcnt(1)
	v_pk_fma_f32 v[42:43], v[188:189], v[50:51], v[42:43]
	v_lshlrev_b32_e32 v44, 16, v49
	s_waitcnt lgkmcnt(0)
	v_pk_fma_f32 v[158:159], v[192:193], v[54:55], v[42:43]
	v_lshlrev_b32_e32 v42, 16, v45
	v_and_b32_e32 v43, 0xffff0000, v45
	v_and_b32_e32 v45, 0xffff0000, v49
	v_pk_fma_f32 v[42:43], v[68:69], v[42:43], v[160:161]
	v_lshlrev_b32_e32 v46, 16, v53
	v_and_b32_e32 v47, 0xffff0000, v53
	v_pk_fma_f32 v[42:43], v[186:187], v[44:45], v[42:43]
	v_lshlrev_b32_e32 v48, 16, v57
	v_and_b32_e32 v49, 0xffff0000, v57
	v_pk_fma_f32 v[42:43], v[190:191], v[46:47], v[42:43]
	v_lshlrev_b32_e32 v54, 16, v22
	v_pk_fma_f32 v[160:161], v[194:195], v[48:49], v[42:43]
	ds_read_b128 v[42:45], v117 offset:33824
	ds_read_b128 v[46:49], v117 offset:33056
	ds_read_b128 v[50:53], v117 offset:33840
	v_and_b32_e32 v55, 0xffff0000, v22
	v_pk_fma_f32 v[162:163], v[166:167], v[196:197], v[58:59]
	v_lshlrev_b32_e32 v22, 16, v23
	s_waitcnt lgkmcnt(2)
	v_pk_fma_f32 v[42:43], v[70:71], v[54:55], v[42:43]
	ds_read_b128 v[54:57], v117 offset:33312
	ds_read_b128 v[58:61], v117 offset:33568
	ds_read_b128 v[62:65], v117 offset:33072
	v_and_b32_e32 v23, 0xffff0000, v23
	v_lshlrev_b32_e32 v66, 16, v26
	v_and_b32_e32 v67, 0xffff0000, v26
	v_lshlrev_b32_e32 v26, 16, v27
	v_and_b32_e32 v27, 0xffff0000, v27
	v_pk_fma_f32 v[22:23], v[72:73], v[22:23], v[44:45]
	v_lshlrev_b32_e32 v74, 16, v30
	v_and_b32_e32 v75, 0xffff0000, v30
	s_waitcnt lgkmcnt(4)
	v_pk_fma_f32 v[42:43], v[46:47], v[66:67], v[42:43]
	ds_read_b128 v[66:69], v117 offset:33328
	v_lshlrev_b32_e32 v30, 16, v31
	v_and_b32_e32 v31, 0xffff0000, v31
	v_pk_fma_f32 v[22:23], v[48:49], v[26:27], v[22:23]
	v_lshlrev_b32_e32 v166, 16, v34
	v_and_b32_e32 v167, 0xffff0000, v34
	s_waitcnt lgkmcnt(3)
	v_pk_fma_f32 v[42:43], v[54:55], v[74:75], v[42:43]
	ds_read_b128 v[74:77], v117 offset:33584
	v_lshlrev_b32_e32 v34, 16, v35
	v_and_b32_e32 v35, 0xffff0000, v35
	v_pk_fma_f32 v[22:23], v[56:57], v[30:31], v[22:23]
	v_lshlrev_b32_e32 v30, 16, v28
	s_waitcnt lgkmcnt(3)
	v_pk_fma_f32 v[26:27], v[60:61], v[34:35], v[22:23]
	v_lshlrev_b32_e32 v22, 16, v24
	v_and_b32_e32 v23, 0xffff0000, v24
	v_and_b32_e32 v31, 0xffff0000, v28
	v_pk_fma_f32 v[22:23], v[38:39], v[22:23], v[50:51]
	v_lshlrev_b32_e32 v34, 16, v32
	v_and_b32_e32 v35, 0xffff0000, v32
	s_waitcnt lgkmcnt(2)
	v_pk_fma_f32 v[22:23], v[62:63], v[30:31], v[22:23]
	v_lshlrev_b32_e32 v44, 16, v36
	v_and_b32_e32 v45, 0xffff0000, v36
	s_waitcnt lgkmcnt(1)
	v_pk_fma_f32 v[22:23], v[66:67], v[34:35], v[22:23]
	v_lshlrev_b32_e32 v24, 16, v29
	s_waitcnt lgkmcnt(0)
	v_pk_fma_f32 v[30:31], v[74:75], v[44:45], v[22:23]
	v_lshlrev_b32_e32 v22, 16, v25
	v_and_b32_e32 v23, 0xffff0000, v25
	v_and_b32_e32 v25, 0xffff0000, v29
	v_pk_fma_f32 v[22:23], v[40:41], v[22:23], v[52:53]
	v_lshlrev_b32_e32 v28, 16, v33
	v_and_b32_e32 v29, 0xffff0000, v33
	v_pk_fma_f32 v[22:23], v[64:65], v[24:25], v[22:23]
	v_lshlrev_b32_e32 v32, 16, v37
	v_and_b32_e32 v33, 0xffff0000, v37
	v_pk_fma_f32 v[22:23], v[68:69], v[28:29], v[22:23]
	v_pk_fma_f32 v[42:43], v[58:59], v[166:167], v[42:43]
	v_pk_fma_f32 v[28:29], v[76:77], v[32:33], v[22:23]
	v_cvt_pk_bf16_f32 v22, v162, v163
	v_cvt_pk_bf16_f32 v23, v164, v165
	v_cvt_pk_bf16_f32 v24, v158, v159
	v_cvt_pk_bf16_f32 v25, v160, v161
	ds_write_b128 v128, v[22:25] offset:44544
	v_cvt_pk_bf16_f32 v22, v42, v43
	v_cvt_pk_bf16_f32 v23, v26, v27
	v_cvt_pk_bf16_f32 v24, v30, v31
	v_cvt_pk_bf16_f32 v25, v28, v29
	ds_write_b128 v129, v[22:25] offset:44544
	v_add_u32_e32 v22, v119, v120
	s_waitcnt lgkmcnt(0)
; DEVI float bf2f(bf16_t h) { return __uint_as_float(((unsigned)h) << 16); }
; template <bool PASS_C>
; DEVI void lru_item(const P& p, int item, int next_item, uint4& u0, uint4& u1, uint4& u2, float& cpre, char* smem) {
;     ...
;     __syncthreads();
;     f32x4 acc[16];
; #pragma unroll
;     for (int n = 0; n < 16; ++n) acc[n] = (f32x4){0.f, 0.f, 0.f, 0.f};
;     {
;         bf16x8 af[2];
; #pragma unroll
;         for (int kk = 0; kk < 2; ++kk) af[kk] = *(const bf16x8*)(ucb + (16 * w + fr) * 128 + (((kk * 4 + fq) ^ (fr & 7)) << 4));
; #pragma unroll
;         for (int n = 0; n < 16; ++n)
; #pragma unroll
;             for (int kk = 0; kk < 2; ++kk) {
;                 const bf16x8 bfr = *(const bf16x8*)(smem + (16 * n + fr) * 128 + (((kk * 4 + fq) ^ (fr & 7)) << 4));
;                 acc[n] = __builtin_amdgcn_mfma_f32_16x16x32_bf16(af[kk], bfr, acc[n], 0, 0, 0);
;             }
;     }
;     float av[4][2][4], bv[4][2][4], apre[4][2], bpre[4][2];
; #pragma unroll
;     for (int nn = 0; nn < 4; ++nn) {
;         const int ch = 16 * nn + fr;
;         float uc[4];
; #pragma unroll
;         for (int j = 0; j < 4; ++j) {
;             const int tl = 16 * w + 4 * fq + j;
;             uc[j] = bf2f(*(const bf16_t*)(ucb + tl * 128 + ((((ch >> 3)) ^ (tl & 7)) << 4) + (ch & 7) * 2));
;         }
; #pragma unroll
;         for (int d = 0; d < 2; ++d) {
;             const float ba = prm[(5 + d) * 64 + ch], bx = prm[(7 + d) * 64 + ch], nsp8 = prm[(9 + d) * 64 + ch];
	v_add_u32_e32 v87, v118, v120
	v_add_u32_e32 v30, v119, v121
	v_add_u32_e32 v89, v118, v121
	ds_read_b128 v[26:29], v22 offset:44544
	ds_read_b128 v[158:161], v30 offset:44544
	ds_read_b32 v93, v122 offset:35072
	ds_read_b128 v[232:235], v87
	ds_read_b128 v[236:239], v89
	ds_read_b128 v[240:243], v87 offset:2048
	ds_read_b128 v[244:247], v89 offset:2048
	ds_read_b128 v[248:251], v87 offset:4096
	ds_read_b128 v[192:195], v89 offset:4096
	ds_read_b128 v[252:255], v87 offset:6144
	ds_read_b128 v[218:221], v89 offset:6144
	s_waitcnt lgkmcnt(4)
	v_mfma_f32_16x16x32_bf16 v[166:169], v[26:29], v[232:235], 0
	ds_read_b128 v[222:225], v87 offset:8192
	ds_read_b128 v[226:229], v89 offset:8192
	ds_read_b128 v[162:165], v87 offset:10240
	ds_read_b128 v[188:191], v89 offset:10240
	v_mfma_f32_16x16x32_bf16 v[62:65], v[26:29], v[240:243], 0
	v_mfma_f32_16x16x32_bf16 v[166:169], v[158:161], v[236:239], v[166:169]
	v_mfma_f32_16x16x32_bf16 v[62:65], v[158:161], v[244:247], v[62:65]
	s_waitcnt lgkmcnt(4)
	v_mfma_f32_16x16x32_bf16 v[46:49], v[26:29], v[248:251], 0
	ds_read_b128 v[232:235], v87 offset:12288
	ds_read_b128 v[236:239], v89 offset:12288
	ds_read_b128 v[240:243], v87 offset:14336
	ds_read_b128 v[244:247], v89 offset:14336
	v_mfma_f32_16x16x32_bf16 v[30:33], v[26:29], v[252:255], 0
	v_mfma_f32_16x16x32_bf16 v[46:49], v[158:161], v[192:195], v[46:49]
	v_mfma_f32_16x16x32_bf16 v[30:33], v[158:161], v[218:221], v[30:33]
	s_waitcnt lgkmcnt(4)
	v_mfma_f32_16x16x32_bf16 v[184:187], v[26:29], v[222:225], 0
	ds_read_b128 v[248:251], v87 offset:16384
	ds_read_b128 v[192:195], v89 offset:16384
	ds_read_b128 v[252:255], v87 offset:18432
	ds_read_b128 v[218:221], v89 offset:18432
	v_mfma_f32_16x16x32_bf16 v[66:69], v[26:29], v[162:165], 0
	v_mfma_f32_16x16x32_bf16 v[184:187], v[158:161], v[226:229], v[184:187]
	v_mfma_f32_16x16x32_bf16 v[66:69], v[158:161], v[188:191], v[66:69]
	s_waitcnt lgkmcnt(4)
	v_mfma_f32_16x16x32_bf16 v[50:53], v[26:29], v[232:235], 0
	ds_read_b128 v[222:225], v87 offset:20480
	ds_read_b128 v[226:229], v89 offset:20480
	ds_read_b128 v[162:165], v87 offset:22528
	ds_read_b128 v[188:191], v89 offset:22528
	v_mfma_f32_16x16x32_bf16 v[34:37], v[26:29], v[240:243], 0
	v_mfma_f32_16x16x32_bf16 v[50:53], v[158:161], v[236:239], v[50:53]
	v_mfma_f32_16x16x32_bf16 v[34:37], v[158:161], v[244:247], v[34:37]
	s_waitcnt lgkmcnt(4)
	v_mfma_f32_16x16x32_bf16 v[70:73], v[26:29], v[248:251], 0
	ds_read_b128 v[232:235], v87 offset:24576
	ds_read_b128 v[236:239], v89 offset:24576
	ds_read_b128 v[240:243], v87 offset:26624
	ds_read_b128 v[244:247], v89 offset:26624
	v_mfma_f32_16x16x32_bf16 v[54:57], v[26:29], v[252:255], 0
	v_mfma_f32_16x16x32_bf16 v[70:73], v[158:161], v[192:195], v[70:73]
	v_mfma_f32_16x16x32_bf16 v[54:57], v[158:161], v[218:221], v[54:57]
	s_waitcnt lgkmcnt(4)
	v_mfma_f32_16x16x32_bf16 v[38:41], v[26:29], v[222:225], 0
	ds_read_b128 v[248:251], v87 offset:28672
	ds_read_b128 v[252:255], v87 offset:30720
	ds_read_b128 v[192:195], v89 offset:28672
	v_mfma_f32_16x16x32_bf16 v[22:25], v[26:29], v[162:165], 0
	v_mfma_f32_16x16x32_bf16 v[38:41], v[158:161], v[226:229], v[38:41]
	v_mfma_f32_16x16x32_bf16 v[22:25], v[158:161], v[188:191], v[22:25]
	s_waitcnt lgkmcnt(3)
	v_mfma_f32_16x16x32_bf16 v[74:77], v[26:29], v[232:235], 0
	v_mfma_f32_16x16x32_bf16 v[58:61], v[26:29], v[240:243], 0
	v_mfma_f32_16x16x32_bf16 v[74:77], v[158:161], v[236:239], v[74:77]
	v_mfma_f32_16x16x32_bf16 v[58:61], v[158:161], v[244:247], v[58:61]
	s_waitcnt lgkmcnt(1)
	v_mfma_f32_16x16x32_bf16 v[42:45], v[26:29], v[248:251], 0
	v_mfma_f32_16x16x32_bf16 v[26:29], v[26:29], v[252:255], 0
	ds_read_b128 v[162:165], v89 offset:30720
	ds_read2st64_b32 v[170:171], v122 offset0:133 offset1:135
	ds_read_u16 v246, v130 offset:44544
	ds_read_u16 v247, v131 offset:44544
	ds_read_u16 v248, v132 offset:44544
	ds_read_u16 v249, v133 offset:44544
	ds_read2st64_b32 v[232:233], v122 offset0:134 offset1:136
	ds_read_b32 v250, v122 offset:35328
	v_add_u32_e32 v217, 64, v122
	ds_read2st64_b32 v[234:235], v217 offset0:133 offset1:135
	ds_read_u16 v251, v134 offset:44544
	ds_read_u16 v252, v135 offset:44544
	ds_read_u16 v253, v136 offset:44544
	ds_read_u16 v254, v137 offset:44544
	ds_read_b32 v255, v122 offset:35136
	v_add_u32_e32 v217, 64, v122
	ds_read2st64_b32 v[236:237], v217 offset0:134 offset1:136
	ds_read_b32 v218, v122 offset:35392
	v_add_u32_e32 v217, 0x80, v122
	ds_read2st64_b32 v[238:239], v217 offset0:133 offset1:135
	ds_read_u16 v219, v138 offset:44544
	ds_read_u16 v220, v139 offset:44544
	ds_read_u16 v221, v140 offset:44544
	ds_read_u16 v222, v141 offset:44544
	ds_read_b32 v223, v122 offset:35200
	v_add_u32_e32 v217, 0x80, v122
	ds_read2st64_b32 v[240:241], v217 offset0:134 offset1:136
	ds_read_b32 v224, v122 offset:35456
	v_add_u32_e32 v217, 0xc0, v122
	ds_read2st64_b32 v[242:243], v217 offset0:133 offset1:135
	ds_read_u16 v225, v142 offset:44544
	ds_read_u16 v226, v143 offset:44544
	ds_read_u16 v227, v144 offset:44544
	ds_read_u16 v228, v145 offset:44544
	ds_read_b32 v229, v122 offset:35264
	v_add_u32_e32 v217, 0xc0, v122
	ds_read2st64_b32 v[244:245], v217 offset0:134 offset1:136
	ds_read_b32 v231, v122 offset:35520
	s_waitcnt lgkmcnt(0)
; template <bool PASS_C>
; DEVI void lru_item(const P& p, int item, int next_item, uint4& u0, uint4& u1, uint4& u2, float& cpre, char* smem) {
;     ...
;         for (int d = 0; d < 2; ++d) {
;             const float ba = prm[(5 + d) * 64 + ch], bx = prm[(7 + d) * 64 + ch], nsp8 = prm[(9 + d) * 64 + ch];
; #pragma unroll
;             for (int j = 0; j < 4; ++j) {
;                 const float r = __builtin_amdgcn_rcpf(1.0f + __builtin_amdgcn_exp2f(__builtin_fmaf(acc[(2 * d) * 4 + nn][j], -LOG2E, ba)));
;                 const float ig = __builtin_amdgcn_rcpf(1.0f + __builtin_amdgcn_exp2f(__builtin_fmaf(acc[(2 * d + 1) * 4 + nn][j], -LOG2E, bx)));
;                 const float a_ = __builtin_amdgcn_exp2f(nsp8 * r);
;                 av[nn][d][j] = a_;
;                 bv[nn][d][j] = __builtin_amdgcn_sqrtf(__builtin_fmaf(-a_, a_, 1.0f)) * ig * uc[j];
;             }
;             float A = 1.f, Bq = 0.f;
;             if (d == 0) {
; #pragma unroll
;                 for (int j = 0; j < 4; ++j) { Bq = av[nn][d][j] * Bq + bv[nn][d][j]; A *= av[nn][d][j]; }
;             } else {
; #pragma unroll
;                 for (int j = 3; j >= 0; --j) { Bq = av[nn][d][j] * Bq + bv[nn][d][j]; A *= av[nn][d][j]; }
;             }
;             float Ag[4], Bg[4];
;             rowgather4(A, Ag); rowgather4(Bq, Bg);
;             float AW = 1.f, BW = 0.f, AP = 1.f, BP = 0.f;
;             if (d == 0) {
; #pragma unroll
;                 for (int g = 0; g < 4; ++g) {
;                     if (g == fq) { AP = AW; BP = BW; }
;                     BW = Ag[g] * BW + Bg[g]; AW *= Ag[g];
;                 }
;             } else {
; #pragma unroll
;                 for (int g = 3; g >= 0; --g) {
;                     if (g == fq) { AP = AW; BP = BW; }
;                     BW = Ag[g] * BW + Bg[g]; AW *= Ag[g];
;                 }
;             }
;             apre[nn][d] = AP; bpre[nn][d] = BP;
;             if (fq == 0) { wagg[((w * 2 + d) * 64 + ch) * 2 + 0] = AW; wagg[((w * 2 + d) * 64 + ch) * 2 + 1] = BW; }
	v_fmamk_f32 v95, v166, 0xbfb8aa3b, v170
	v_exp_f32_e32 v95, v95
	v_mfma_f32_16x16x32_bf16 v[42:45], v[158:161], v[192:195], v[42:45]
	v_fmamk_f32 v99, v168, 0xbfb8aa3b, v170
	v_fmamk_f32 v101, v186, 0xbfb8aa3b, v171
	v_exp_f32_e32 v99, v99
	v_mfma_f32_16x16x32_bf16 v[26:29], v[158:161], v[162:165], v[26:29]
	v_lshlrev_b32_e32 v164, 16, v246
	v_lshlrev_b32_e32 v161, 16, v247
	v_add_f32_e32 v87, 1.0, v95
	v_fmamk_f32 v89, v184, 0xbfb8aa3b, v171
	v_exp_f32_e32 v89, v89
	v_rcp_f32_e32 v87, v87
	v_lshlrev_b32_e32 v162, 16, v248
	v_add_f32_e32 v95, 1.0, v89
	v_mul_f32_e32 v87, v93, v87
	v_exp_f32_e32 v89, v87
	v_rcp_f32_e32 v87, v95
	v_fmamk_f32 v95, v167, 0xbfb8aa3b, v170
	v_exp_f32_e32 v95, v95
	v_lshlrev_b32_e32 v163, 16, v249
	v_fma_f32 v97, -v89, v89, 1.0
	v_sqrt_f32_e32 v97, v97
	v_add_f32_e32 v91, 1.0, v95
	v_rcp_f32_e32 v91, v91
	v_fmamk_f32 v95, v185, 0xbfb8aa3b, v171
	v_exp_f32_e32 v95, v95
	v_mul_f32_e32 v87, v87, v97
	v_mul_f32_e32 v91, v93, v91
	v_exp_f32_e32 v91, v91
	v_add_f32_e32 v95, 1.0, v95
	v_rcp_f32_e32 v95, v95
	v_exp_f32_e32 v101, v101
	v_fma_f32 v97, -v91, v91, 1.0
	v_sqrt_f32_e32 v97, v97
	v_fmamk_f32 v171, v187, 0xbfb8aa3b, v171
	v_exp_f32_e32 v105, v171
	v_mul_f32_e32 v87, v87, v164
	v_mul_f32_e32 v97, v95, v97
	v_add_f32_e32 v95, 1.0, v99
	v_add_f32_e32 v99, 1.0, v101
	v_fmamk_f32 v101, v169, 0xbfb8aa3b, v170
	v_exp_f32_e32 v101, v101
	v_rcp_f32_e32 v95, v95
	v_rcp_f32_e32 v99, v99
	v_add_f32_e32 v101, 1.0, v101
	v_rcp_f32_e32 v101, v101
	v_mul_f32_e32 v95, v93, v95
	v_exp_f32_e32 v95, v95
	v_mul_f32_e32 v93, v93, v101
	v_exp_f32_e32 v101, v93
	v_add_f32_e32 v93, 1.0, v105
	v_fma_f32 v103, -v95, v95, 1.0
	v_rcp_f32_e32 v105, v93
	v_fma_f32 v93, -v101, v101, 1.0
	v_sqrt_f32_e32 v103, v103
	v_sqrt_f32_e32 v157, v93
	v_mul_f32_e32 v93, v97, v161
	v_mul_f32_e32 v97, v99, v103
	v_mul_f32_e32 v99, v105, v157
	v_fma_f32 v105, 0, v89, v87
	v_mul_f32_e32 v97, v97, v162
	v_mul_f32_e32 v103, v89, v91
	v_fma_f32 v105, v91, v105, v93
	v_mul_f32_e32 v99, v99, v163
	v_mul_f32_e32 v103, v95, v103
	v_fma_f32 v105, v95, v105, v97
	v_mul_f32_e32 v103, v101, v103
	v_fma_f32 v105, v101, v105, v99
	v_mov_b32_e32 v159, v103
	v_mov_b32_e32 v157, v105
	s_nop 0
	v_permlane16_swap_b32_e32 v103, v159
	v_permlane16_swap_b32_e32 v105, v157
	v_mov_b32_e32 v160, v103
	v_mov_b32_e32 v158, v105
	s_nop 0
	v_permlane32_swap_b32_e32 v103, v160
	v_mov_b32_e32 v165, v159
	v_permlane32_swap_b32_e32 v105, v158
	v_mov_b32_e32 v166, v157
	v_permlane32_swap_b32_e32 v159, v165
	s_nop 0
	v_permlane32_swap_b32_e32 v157, v166
	v_fmac_f32_e32 v157, v105, v159
	v_mul_f32_e32 v159, v103, v159
	v_fmac_f32_e32 v158, v157, v160
	v_mul_f32_e32 v160, v159, v160
	s_and_saveexec_b64 s[28:29], s[10:11]
	v_mul_f32_e32 v167, v158, v165
	v_mul_f32_e32 v168, v160, v165
	v_add_f32_e32 v169, v167, v166
	ds_write_b64 v149, v[168:169] offset:52736
	s_or_b64 exec, exec, s[28:29]
	v_fmamk_f32 v70, v70, 0xbfb8aa3b, v232
	v_exp_f32_e32 v70, v70
	v_fmamk_f32 v71, v71, 0xbfb8aa3b, v232
	v_exp_f32_e32 v71, v71
	v_fmamk_f32 v74, v74, 0xbfb8aa3b, v233
	v_add_f32_e32 v70, 1.0, v70
	v_rcp_f32_e32 v70, v70
	v_add_f32_e32 v71, 1.0, v71
	v_exp_f32_e32 v74, v74
	v_rcp_f32_e32 v71, v71
	v_mul_f32_e32 v70, v250, v70
	v_exp_f32_e32 v70, v70
	v_fmamk_f32 v75, v75, 0xbfb8aa3b, v233
	v_add_f32_e32 v74, 1.0, v74
	v_mul_f32_e32 v71, v250, v71
	v_fma_f32 v168, -v70, v70, 1.0
	v_fmamk_f32 v72, v72, 0xbfb8aa3b, v232
	v_fmamk_f32 v73, v73, 0xbfb8aa3b, v232
	v_exp_f32_e32 v75, v75
	v_rcp_f32_e32 v74, v74
	v_exp_f32_e32 v71, v71
	v_sqrt_f32_e32 v168, v168
	v_exp_f32_e32 v72, v72
	v_exp_f32_e32 v73, v73
	v_add_f32_e32 v75, 1.0, v75
	v_fma_f32 v169, -v71, v71, 1.0
	v_mul_f32_e32 v74, v74, v168
	v_fmamk_f32 v76, v76, 0xbfb8aa3b, v233
	v_add_f32_e32 v72, 1.0, v72
	v_add_f32_e32 v73, 1.0, v73
	v_rcp_f32_e32 v75, v75
	v_mul_f32_e32 v74, v74, v164
	v_sqrt_f32_e32 v164, v169
	v_exp_f32_e32 v76, v76
	v_rcp_f32_e32 v72, v72
	v_rcp_f32_e32 v73, v73
	v_fmamk_f32 v167, v77, 0xbfb8aa3b, v233
	v_mul_f32_e32 v164, v75, v164
	v_add_f32_e32 v75, 1.0, v76
	v_mul_f32_e32 v72, v250, v72
	v_exp_f32_e32 v77, v167
	v_mul_f32_e32 v73, v250, v73
	v_exp_f32_e32 v72, v72
	v_rcp_f32_e32 v76, v75
	v_exp_f32_e32 v75, v73
	v_add_f32_e32 v73, 1.0, v77
	v_fma_f32 v166, -v72, v72, 1.0
	v_rcp_f32_e32 v77, v73
	v_fma_f32 v73, -v75, v75, 1.0
	v_sqrt_f32_e32 v165, v166
	v_sqrt_f32_e32 v166, v73
	v_mul_f32_e32 v73, v164, v161
	v_mul_f32_e32 v161, v75, v72
	v_mul_f32_e32 v76, v76, v165
	v_mul_f32_e32 v77, v77, v166
	v_mul_f32_e32 v77, v77, v163
	v_mul_f32_e32 v161, v71, v161
	v_mul_f32_e32 v76, v76, v162
	v_mul_f32_e32 v165, v70, v161
	v_fma_f32 v161, 0, v75, v77
	v_fma_f32 v161, v72, v161, v76
	v_fma_f32 v161, v71, v161, v73
	v_fma_f32 v168, v70, v161, v74
	v_mov_b32_e32 v167, v165
	v_mov_b32_e32 v161, v168
	s_nop 0
	v_permlane16_swap_b32_e32 v165, v167
	v_permlane16_swap_b32_e32 v168, v161
	v_mov_b32_e32 v162, v167
	v_mov_b32_e32 v164, v161
	v_mov_b32_e32 v166, v165
	v_permlane32_swap_b32_e32 v167, v162
	v_mov_b32_e32 v163, v168
	v_permlane32_swap_b32_e32 v161, v164
	v_permlane32_swap_b32_e32 v165, v166
	v_permlane32_swap_b32_e32 v168, v163
	v_fmac_f32_e32 v163, v164, v166
	v_mul_f32_e32 v166, v166, v162
	v_fmac_f32_e32 v161, v163, v167
	v_mul_f32_e32 v167, v166, v167
	s_and_saveexec_b64 s[28:29], s[10:11]
	v_mul_f32_e32 v169, v161, v165
	v_mul_f32_e32 v170, v167, v165
	v_add_f32_e32 v171, v169, v168
	ds_write_b64 v149, v[170:171] offset:53248
	s_or_b64 exec, exec, s[28:29]
	v_lshlrev_b32_e32 v185, 16, v251
	v_lshlrev_b32_e32 v183, 16, v252
	v_lshlrev_b32_e32 v177, 16, v253
	v_fmamk_f32 v62, v62, 0xbfb8aa3b, v234
	v_exp_f32_e32 v62, v62
; template <bool PASS_C>
; DEVI void lru_item(const P& p, int item, int next_item, uint4& u0, uint4& u1, uint4& u2, float& cpre, char* smem) {
;     ...
;         for (int d = 0; d < 2; ++d) {
;             const float ba = prm[(5 + d) * 64 + ch], bx = prm[(7 + d) * 64 + ch], nsp8 = prm[(9 + d) * 64 + ch];
; #pragma unroll
;             for (int j = 0; j < 4; ++j) {
;                 const float r = __builtin_amdgcn_rcpf(1.0f + __builtin_amdgcn_exp2f(__builtin_fmaf(acc[(2 * d) * 4 + nn][j], -LOG2E, ba)));
;                 const float ig = __builtin_amdgcn_rcpf(1.0f + __builtin_amdgcn_exp2f(__builtin_fmaf(acc[(2 * d + 1) * 4 + nn][j], -LOG2E, bx)));
;                 const float a_ = __builtin_amdgcn_exp2f(nsp8 * r);
;                 av[nn][d][j] = a_;
;                 bv[nn][d][j] = __builtin_amdgcn_sqrtf(__builtin_fmaf(-a_, a_, 1.0f)) * ig * uc[j];
;             }
;             float A = 1.f, Bq = 0.f;
;             if (d == 0) {
; #pragma unroll
;                 for (int j = 0; j < 4; ++j) { Bq = av[nn][d][j] * Bq + bv[nn][d][j]; A *= av[nn][d][j]; }
;             } else {
; #pragma unroll
;                 for (int j = 3; j >= 0; --j) { Bq = av[nn][d][j] * Bq + bv[nn][d][j]; A *= av[nn][d][j]; }
;             }
;             float Ag[4], Bg[4];
;             rowgather4(A, Ag); rowgather4(Bq, Bg);
;             float AW = 1.f, BW = 0.f, AP = 1.f, BP = 0.f;
;             if (d == 0) {
; #pragma unroll
;                 for (int g = 0; g < 4; ++g) {
;                     if (g == fq) { AP = AW; BP = BW; }
;                     BW = Ag[g] * BW + Bg[g]; AW *= Ag[g];
;                 }
;             } else {
; #pragma unroll
;                 for (int g = 3; g >= 0; --g) {
;                     if (g == fq) { AP = AW; BP = BW; }
;                     BW = Ag[g] * BW + Bg[g]; AW *= Ag[g];
;                 }
;             }
;             apre[nn][d] = AP; bpre[nn][d] = BP;
;             if (fq == 0) { wagg[((w * 2 + d) * 64 + ch) * 2 + 0] = AW; wagg[((w * 2 + d) * 64 + ch) * 2 + 1] = BW; }
	v_fmamk_f32 v63, v63, 0xbfb8aa3b, v234
	v_fmamk_f32 v66, v66, 0xbfb8aa3b, v235
	v_exp_f32_e32 v63, v63
	v_add_f32_e32 v62, 1.0, v62
	v_rcp_f32_e32 v62, v62
	v_exp_f32_e32 v66, v66
	v_add_f32_e32 v63, 1.0, v63
	v_rcp_f32_e32 v63, v63
	v_mul_f32_e32 v62, v255, v62
	v_add_f32_e32 v165, 1.0, v66
	v_exp_f32_e32 v66, v62
	v_rcp_f32_e32 v62, v165
	v_fmamk_f32 v67, v67, 0xbfb8aa3b, v235
	v_mul_f32_e32 v63, v255, v63
	v_fma_f32 v165, -v66, v66, 1.0
	v_sqrt_f32_e32 v165, v165
	v_exp_f32_e32 v67, v67
	v_exp_f32_e32 v63, v63
	v_fmamk_f32 v64, v64, 0xbfb8aa3b, v234
	v_exp_f32_e32 v64, v64
	v_mul_f32_e32 v62, v62, v165
	v_add_f32_e32 v67, 1.0, v67
	v_fma_f32 v165, -v63, v63, 1.0
	v_rcp_f32_e32 v67, v67
	v_sqrt_f32_e32 v165, v165
	v_add_f32_e32 v64, 1.0, v64
	v_rcp_f32_e32 v64, v64
	v_fmamk_f32 v65, v65, 0xbfb8aa3b, v234
	v_mul_f32_e32 v67, v67, v165
	v_exp_f32_e32 v165, v65
	v_mul_f32_e32 v64, v255, v64
	v_exp_f32_e32 v65, v64
	v_fmamk_f32 v68, v68, 0xbfb8aa3b, v235
	v_add_f32_e32 v64, 1.0, v165
	v_rcp_f32_e32 v64, v64
	v_fmamk_f32 v169, v69, 0xbfb8aa3b, v235
	v_exp_f32_e32 v168, v169
	v_exp_f32_e32 v68, v68
	v_mul_f32_e32 v64, v255, v64
	v_exp_f32_e32 v69, v64
	v_add_f32_e32 v64, 1.0, v168
	v_add_f32_e32 v68, 1.0, v68
	v_fma_f32 v165, -v65, v65, 1.0
	v_rcp_f32_e32 v168, v64
	v_fma_f32 v64, -v69, v69, 1.0
	v_rcp_f32_e32 v68, v68
	v_sqrt_f32_e32 v165, v165
	v_sqrt_f32_e32 v169, v64
	v_mul_f32_e32 v62, v62, v185
	v_mul_f32_e32 v64, v67, v183
	v_mul_f32_e32 v67, v68, v165
	v_mul_f32_e32 v68, v168, v169
	v_fma_f32 v168, 0, v66, v62
	v_lshlrev_b32_e32 v184, 16, v254
	v_mul_f32_e32 v67, v67, v177
	v_mul_f32_e32 v165, v66, v63
	v_fma_f32 v168, v63, v168, v64
	v_mul_f32_e32 v68, v68, v184
	v_mul_f32_e32 v165, v65, v165
	v_fma_f32 v168, v65, v168, v67
	v_mul_f32_e32 v165, v69, v165
	v_fma_f32 v168, v69, v168, v68
	v_mov_b32_e32 v171, v165
	v_mov_b32_e32 v169, v168
	s_nop 0
	v_permlane16_swap_b32_e32 v165, v171
	v_permlane16_swap_b32_e32 v168, v169
	v_mov_b32_e32 v173, v165
	v_mov_b32_e32 v170, v168
	s_nop 0
	v_permlane32_swap_b32_e32 v165, v173
	v_mov_b32_e32 v187, v171
	v_permlane32_swap_b32_e32 v168, v170
	v_mov_b32_e32 v188, v169
	v_permlane32_swap_b32_e32 v171, v187
	s_nop 0
	v_permlane32_swap_b32_e32 v169, v188
	v_fmac_f32_e32 v169, v168, v171
	v_mul_f32_e32 v171, v165, v171
	v_fmac_f32_e32 v170, v169, v173
	v_mul_f32_e32 v173, v171, v173
	s_and_saveexec_b64 s[28:29], s[10:11]
	v_mul_f32_e32 v189, v170, v187
	v_mul_f32_e32 v190, v173, v187
	v_add_f32_e32 v191, v189, v188
	ds_write_b64 v150, v[190:191] offset:52736
	s_or_b64 exec, exec, s[28:29]
	v_fmamk_f32 v54, v54, 0xbfb8aa3b, v236
	v_exp_f32_e32 v54, v54
	v_fmamk_f32 v55, v55, 0xbfb8aa3b, v236
	v_exp_f32_e32 v55, v55
	v_fmamk_f32 v58, v58, 0xbfb8aa3b, v237
	v_add_f32_e32 v54, 1.0, v54
	v_rcp_f32_e32 v54, v54
	v_add_f32_e32 v55, 1.0, v55
	v_exp_f32_e32 v58, v58
	v_rcp_f32_e32 v55, v55
	v_mul_f32_e32 v54, v218, v54
	v_exp_f32_e32 v54, v54
	v_fmamk_f32 v56, v56, 0xbfb8aa3b, v236
	v_fmamk_f32 v59, v59, 0xbfb8aa3b, v237
	v_add_f32_e32 v58, 1.0, v58
	v_mul_f32_e32 v55, v218, v55
	v_fma_f32 v189, -v54, v54, 1.0
	v_exp_f32_e32 v56, v56
	v_fmamk_f32 v57, v57, 0xbfb8aa3b, v236
	v_exp_f32_e32 v59, v59
	v_rcp_f32_e32 v58, v58
	v_exp_f32_e32 v55, v55
	v_sqrt_f32_e32 v189, v189
	v_exp_f32_e32 v57, v57
	v_add_f32_e32 v56, 1.0, v56
	v_add_f32_e32 v59, 1.0, v59
	v_fma_f32 v190, -v55, v55, 1.0
	v_mul_f32_e32 v58, v58, v189
	v_fmamk_f32 v60, v60, 0xbfb8aa3b, v237
	v_rcp_f32_e32 v56, v56
	v_add_f32_e32 v57, 1.0, v57
	v_rcp_f32_e32 v59, v59
	v_mul_f32_e32 v58, v58, v185
	v_sqrt_f32_e32 v185, v190
	v_exp_f32_e32 v60, v60
	v_rcp_f32_e32 v57, v57
	v_mul_f32_e32 v56, v218, v56
	v_fmamk_f32 v187, v61, 0xbfb8aa3b, v237
	v_mul_f32_e32 v185, v59, v185
	v_add_f32_e32 v59, 1.0, v60
	v_exp_f32_e32 v56, v56
	v_exp_f32_e32 v61, v187
	v_mul_f32_e32 v57, v218, v57
	v_rcp_f32_e32 v60, v59
	v_exp_f32_e32 v59, v57
	v_fma_f32 v186, -v56, v56, 1.0
	v_add_f32_e32 v57, 1.0, v61
	v_sqrt_f32_e32 v186, v186
	v_rcp_f32_e32 v61, v57
	v_fma_f32 v57, -v59, v59, 1.0
	v_sqrt_f32_e32 v187, v57
	v_mul_f32_e32 v60, v60, v186
	v_mul_f32_e32 v60, v60, v177
	v_mul_f32_e32 v177, v59, v56
	v_mul_f32_e32 v61, v61, v187
	v_mul_f32_e32 v61, v61, v184
	v_mul_f32_e32 v177, v55, v177
	v_mul_f32_e32 v186, v54, v177
	v_fma_f32 v177, 0, v59, v61
	v_mul_f32_e32 v57, v185, v183
	v_fma_f32 v177, v56, v177, v60
	v_fma_f32 v177, v55, v177, v57
	v_fma_f32 v189, v54, v177, v58
	v_mov_b32_e32 v188, v186
	v_mov_b32_e32 v177, v189
	s_nop 0
	v_permlane16_swap_b32_e32 v186, v188
	v_permlane16_swap_b32_e32 v189, v177
	v_mov_b32_e32 v183, v188
	v_mov_b32_e32 v185, v177
	v_mov_b32_e32 v187, v186
	v_permlane32_swap_b32_e32 v188, v183
	v_mov_b32_e32 v184, v189
	v_permlane32_swap_b32_e32 v177, v185
	v_permlane32_swap_b32_e32 v186, v187
	v_permlane32_swap_b32_e32 v189, v184
	v_fmac_f32_e32 v184, v185, v187
	v_mul_f32_e32 v187, v187, v183
	v_fmac_f32_e32 v177, v184, v188
	v_mul_f32_e32 v188, v187, v188
	s_and_saveexec_b64 s[28:29], s[10:11]
	v_mul_f32_e32 v191, v177, v186
	v_mul_f32_e32 v190, v188, v186
	v_add_f32_e32 v191, v191, v189
	ds_write_b64 v150, v[190:191] offset:53248
	s_or_b64 exec, exec, s[28:29]
	v_lshlrev_b32_e32 v197, 16, v219
	v_lshlrev_b32_e32 v195, 16, v220
	v_lshlrev_b32_e32 v194, 16, v221
	v_fmamk_f32 v46, v46, 0xbfb8aa3b, v238
	v_exp_f32_e32 v46, v46
	v_fmamk_f32 v47, v47, 0xbfb8aa3b, v238
	v_fmamk_f32 v50, v50, 0xbfb8aa3b, v239
	v_exp_f32_e32 v47, v47
	v_add_f32_e32 v46, 1.0, v46
	v_rcp_f32_e32 v46, v46
	v_exp_f32_e32 v50, v50
	v_add_f32_e32 v47, 1.0, v47
	v_rcp_f32_e32 v47, v47
	v_mul_f32_e32 v46, v223, v46
	v_add_f32_e32 v186, 1.0, v50
	v_exp_f32_e32 v50, v46
; template <bool PASS_C>
; DEVI void lru_item(const P& p, int item, int next_item, uint4& u0, uint4& u1, uint4& u2, float& cpre, char* smem) {
;     ...
;         for (int d = 0; d < 2; ++d) {
;             const float ba = prm[(5 + d) * 64 + ch], bx = prm[(7 + d) * 64 + ch], nsp8 = prm[(9 + d) * 64 + ch];
; #pragma unroll
;             for (int j = 0; j < 4; ++j) {
;                 const float r = __builtin_amdgcn_rcpf(1.0f + __builtin_amdgcn_exp2f(__builtin_fmaf(acc[(2 * d) * 4 + nn][j], -LOG2E, ba)));
;                 const float ig = __builtin_amdgcn_rcpf(1.0f + __builtin_amdgcn_exp2f(__builtin_fmaf(acc[(2 * d + 1) * 4 + nn][j], -LOG2E, bx)));
;                 const float a_ = __builtin_amdgcn_exp2f(nsp8 * r);
;                 av[nn][d][j] = a_;
;                 bv[nn][d][j] = __builtin_amdgcn_sqrtf(__builtin_fmaf(-a_, a_, 1.0f)) * ig * uc[j];
;             }
;             float A = 1.f, Bq = 0.f;
;             if (d == 0) {
; #pragma unroll
;                 for (int j = 0; j < 4; ++j) { Bq = av[nn][d][j] * Bq + bv[nn][d][j]; A *= av[nn][d][j]; }
;             } else {
; #pragma unroll
;                 for (int j = 3; j >= 0; --j) { Bq = av[nn][d][j] * Bq + bv[nn][d][j]; A *= av[nn][d][j]; }
;             }
;             float Ag[4], Bg[4];
;             rowgather4(A, Ag); rowgather4(Bq, Bg);
;             float AW = 1.f, BW = 0.f, AP = 1.f, BP = 0.f;
;             if (d == 0) {
; #pragma unroll
;                 for (int g = 0; g < 4; ++g) {
;                     if (g == fq) { AP = AW; BP = BW; }
;                     BW = Ag[g] * BW + Bg[g]; AW *= Ag[g];
;                 }
;             } else {
; #pragma unroll
;                 for (int g = 3; g >= 0; --g) {
;                     if (g == fq) { AP = AW; BP = BW; }
;                     BW = Ag[g] * BW + Bg[g]; AW *= Ag[g];
;                 }
;             }
;             apre[nn][d] = AP; bpre[nn][d] = BP;
;             if (fq == 0) { wagg[((w * 2 + d) * 64 + ch) * 2 + 0] = AW; wagg[((w * 2 + d) * 64 + ch) * 2 + 1] = BW; }
	v_rcp_f32_e32 v46, v186
	v_fmamk_f32 v51, v51, 0xbfb8aa3b, v239
	v_mul_f32_e32 v47, v223, v47
	v_fma_f32 v186, -v50, v50, 1.0
	v_sqrt_f32_e32 v186, v186
	v_exp_f32_e32 v51, v51
	v_exp_f32_e32 v47, v47
	v_fmamk_f32 v48, v48, 0xbfb8aa3b, v238
	v_exp_f32_e32 v48, v48
	v_mul_f32_e32 v46, v46, v186
	v_add_f32_e32 v51, 1.0, v51
	v_fma_f32 v186, -v47, v47, 1.0
	v_rcp_f32_e32 v51, v51
	v_sqrt_f32_e32 v186, v186
	v_add_f32_e32 v48, 1.0, v48
	v_rcp_f32_e32 v48, v48
	v_fmamk_f32 v49, v49, 0xbfb8aa3b, v238
	v_mul_f32_e32 v51, v51, v186
	v_exp_f32_e32 v186, v49
	v_mul_f32_e32 v48, v223, v48
	v_exp_f32_e32 v49, v48
	v_fmamk_f32 v52, v52, 0xbfb8aa3b, v239
	v_add_f32_e32 v48, 1.0, v186
	v_rcp_f32_e32 v48, v48
	v_fmamk_f32 v191, v53, 0xbfb8aa3b, v239
	v_exp_f32_e32 v189, v191
	v_exp_f32_e32 v52, v52
	v_mul_f32_e32 v48, v223, v48
	v_exp_f32_e32 v53, v48
	v_add_f32_e32 v48, 1.0, v189
	v_add_f32_e32 v52, 1.0, v52
	v_fma_f32 v186, -v49, v49, 1.0
	v_rcp_f32_e32 v189, v48
	v_fma_f32 v48, -v53, v53, 1.0
	v_rcp_f32_e32 v52, v52
	v_sqrt_f32_e32 v186, v186
	v_sqrt_f32_e32 v190, v48
	v_mul_f32_e32 v46, v46, v197
	v_mul_f32_e32 v48, v51, v195
	v_mul_f32_e32 v51, v52, v186
	v_mul_f32_e32 v52, v189, v190
	v_fma_f32 v189, 0, v50, v46
	v_lshlrev_b32_e32 v196, 16, v222
	v_mul_f32_e32 v51, v51, v194
	v_mul_f32_e32 v186, v50, v47
	v_fma_f32 v189, v47, v189, v48
	v_mul_f32_e32 v52, v52, v196
	v_mul_f32_e32 v186, v49, v186
	v_fma_f32 v189, v49, v189, v51
	v_mul_f32_e32 v186, v53, v186
	v_fma_f32 v189, v53, v189, v52
	v_mov_b32_e32 v192, v186
	v_mov_b32_e32 v190, v189
	s_nop 0
	v_permlane16_swap_b32_e32 v186, v192
	v_permlane16_swap_b32_e32 v189, v190
	v_mov_b32_e32 v193, v186
	v_mov_b32_e32 v191, v189
	s_nop 0
	v_permlane32_swap_b32_e32 v186, v193
	v_mov_b32_e32 v199, v192
	v_permlane32_swap_b32_e32 v189, v191
	v_mov_b32_e32 v200, v190
	v_permlane32_swap_b32_e32 v192, v199
	s_nop 0
	v_permlane32_swap_b32_e32 v190, v200
	v_fmac_f32_e32 v190, v189, v192
	v_mul_f32_e32 v192, v186, v192
	v_fmac_f32_e32 v191, v190, v193
	v_mul_f32_e32 v193, v192, v193
	s_and_saveexec_b64 s[28:29], s[10:11]
	v_mul_f32_e32 v201, v191, v199
	v_mul_f32_e32 v202, v193, v199
	v_add_f32_e32 v203, v201, v200
	ds_write_b64 v151, v[202:203] offset:52736
	s_or_b64 exec, exec, s[28:29]
	v_fmamk_f32 v38, v38, 0xbfb8aa3b, v240
	v_exp_f32_e32 v38, v38
	v_fmamk_f32 v39, v39, 0xbfb8aa3b, v240
	v_exp_f32_e32 v39, v39
	v_fmamk_f32 v42, v42, 0xbfb8aa3b, v241
	v_add_f32_e32 v38, 1.0, v38
	v_rcp_f32_e32 v38, v38
	v_add_f32_e32 v39, 1.0, v39
	v_exp_f32_e32 v42, v42
	v_rcp_f32_e32 v39, v39
	v_mul_f32_e32 v38, v224, v38
	v_exp_f32_e32 v38, v38
	v_fmamk_f32 v40, v40, 0xbfb8aa3b, v240
	v_fmamk_f32 v43, v43, 0xbfb8aa3b, v241
	v_add_f32_e32 v42, 1.0, v42
	v_mul_f32_e32 v39, v224, v39
	v_fma_f32 v201, -v38, v38, 1.0
	v_exp_f32_e32 v40, v40
	v_fmamk_f32 v41, v41, 0xbfb8aa3b, v240
	v_exp_f32_e32 v43, v43
	v_rcp_f32_e32 v42, v42
	v_exp_f32_e32 v39, v39
	v_sqrt_f32_e32 v201, v201
	v_exp_f32_e32 v41, v41
	v_add_f32_e32 v40, 1.0, v40
	v_add_f32_e32 v43, 1.0, v43
	v_fma_f32 v202, -v39, v39, 1.0
	v_mul_f32_e32 v42, v42, v201
	v_fmamk_f32 v44, v44, 0xbfb8aa3b, v241
	v_rcp_f32_e32 v40, v40
	v_add_f32_e32 v41, 1.0, v41
	v_rcp_f32_e32 v43, v43
	v_mul_f32_e32 v42, v42, v197
	v_sqrt_f32_e32 v197, v202
	v_exp_f32_e32 v44, v44
	v_rcp_f32_e32 v41, v41
	v_mul_f32_e32 v40, v224, v40
	v_fmamk_f32 v199, v45, 0xbfb8aa3b, v241
	v_mul_f32_e32 v197, v43, v197
	v_add_f32_e32 v43, 1.0, v44
	v_exp_f32_e32 v40, v40
	v_exp_f32_e32 v45, v199
	v_mul_f32_e32 v41, v224, v41
	v_rcp_f32_e32 v44, v43
	v_exp_f32_e32 v43, v41
	v_fma_f32 v198, -v40, v40, 1.0
	v_add_f32_e32 v41, 1.0, v45
	v_sqrt_f32_e32 v198, v198
	v_rcp_f32_e32 v45, v41
	v_fma_f32 v41, -v43, v43, 1.0
	v_sqrt_f32_e32 v199, v41
	v_mul_f32_e32 v44, v44, v198
	v_mul_f32_e32 v44, v44, v194
	v_mul_f32_e32 v194, v43, v40
	v_mul_f32_e32 v45, v45, v199
	v_mul_f32_e32 v45, v45, v196
	v_mul_f32_e32 v194, v39, v194
	v_mul_f32_e32 v198, v38, v194
	v_fma_f32 v194, 0, v43, v45
	v_mul_f32_e32 v41, v197, v195
	v_fma_f32 v194, v40, v194, v44
	v_fma_f32 v194, v39, v194, v41
	v_fma_f32 v200, v38, v194, v42
	v_mov_b32_e32 v201, v198
	v_mov_b32_e32 v194, v200
	s_nop 0
	v_permlane16_swap_b32_e32 v198, v201
	v_permlane16_swap_b32_e32 v200, v194
	v_mov_b32_e32 v195, v201
	v_mov_b32_e32 v197, v194
	v_mov_b32_e32 v199, v198
	v_permlane32_swap_b32_e32 v201, v195
	v_mov_b32_e32 v196, v200
	v_permlane32_swap_b32_e32 v194, v197
	v_permlane32_swap_b32_e32 v198, v199
	v_permlane32_swap_b32_e32 v200, v196
	v_fmac_f32_e32 v196, v197, v199
	v_mul_f32_e32 v199, v199, v195
	v_fmac_f32_e32 v194, v196, v201
	v_mul_f32_e32 v201, v199, v201
	s_and_saveexec_b64 s[28:29], s[10:11]
	v_mul_f32_e32 v203, v194, v198
	v_mul_f32_e32 v202, v201, v198
	v_add_f32_e32 v203, v203, v200
	ds_write_b64 v151, v[202:203] offset:53248
	s_or_b64 exec, exec, s[28:29]
	v_lshlrev_b32_e32 v209, 16, v225
	v_lshlrev_b32_e32 v207, 16, v226
	v_lshlrev_b32_e32 v206, 16, v227
	v_fmamk_f32 v30, v30, 0xbfb8aa3b, v242
	v_exp_f32_e32 v30, v30
	v_fmamk_f32 v31, v31, 0xbfb8aa3b, v242
	v_fmamk_f32 v34, v34, 0xbfb8aa3b, v243
	v_exp_f32_e32 v31, v31
	v_add_f32_e32 v30, 1.0, v30
	v_rcp_f32_e32 v30, v30
	v_exp_f32_e32 v34, v34
	v_add_f32_e32 v31, 1.0, v31
	v_rcp_f32_e32 v31, v31
	v_mul_f32_e32 v30, v229, v30
	v_add_f32_e32 v198, 1.0, v34
	v_exp_f32_e32 v34, v30
	v_rcp_f32_e32 v30, v198
	v_fmamk_f32 v35, v35, 0xbfb8aa3b, v243
	v_mul_f32_e32 v31, v229, v31
	v_fma_f32 v198, -v34, v34, 1.0
	v_sqrt_f32_e32 v198, v198
	v_exp_f32_e32 v35, v35
	v_exp_f32_e32 v31, v31
	v_fmamk_f32 v32, v32, 0xbfb8aa3b, v242
	v_exp_f32_e32 v32, v32
	v_mul_f32_e32 v30, v30, v198
	v_add_f32_e32 v35, 1.0, v35
; template <bool PASS_C>
; DEVI void lru_item(const P& p, int item, int next_item, uint4& u0, uint4& u1, uint4& u2, float& cpre, char* smem) {
;     ...
;         for (int d = 0; d < 2; ++d) {
;             const float ba = prm[(5 + d) * 64 + ch], bx = prm[(7 + d) * 64 + ch], nsp8 = prm[(9 + d) * 64 + ch];
; #pragma unroll
;             for (int j = 0; j < 4; ++j) {
;                 const float r = __builtin_amdgcn_rcpf(1.0f + __builtin_amdgcn_exp2f(__builtin_fmaf(acc[(2 * d) * 4 + nn][j], -LOG2E, ba)));
;                 const float ig = __builtin_amdgcn_rcpf(1.0f + __builtin_amdgcn_exp2f(__builtin_fmaf(acc[(2 * d + 1) * 4 + nn][j], -LOG2E, bx)));
;                 const float a_ = __builtin_amdgcn_exp2f(nsp8 * r);
;                 av[nn][d][j] = a_;
;                 bv[nn][d][j] = __builtin_amdgcn_sqrtf(__builtin_fmaf(-a_, a_, 1.0f)) * ig * uc[j];
;             }
;             float A = 1.f, Bq = 0.f;
;             if (d == 0) {
; #pragma unroll
;                 for (int j = 0; j < 4; ++j) { Bq = av[nn][d][j] * Bq + bv[nn][d][j]; A *= av[nn][d][j]; }
;             } else {
; #pragma unroll
;                 for (int j = 3; j >= 0; --j) { Bq = av[nn][d][j] * Bq + bv[nn][d][j]; A *= av[nn][d][j]; }
;             }
;             float Ag[4], Bg[4];
;             rowgather4(A, Ag); rowgather4(Bq, Bg);
;             float AW = 1.f, BW = 0.f, AP = 1.f, BP = 0.f;
;             if (d == 0) {
; #pragma unroll
;                 for (int g = 0; g < 4; ++g) {
;                     if (g == fq) { AP = AW; BP = BW; }
;                     BW = Ag[g] * BW + Bg[g]; AW *= Ag[g];
;                 }
;             } else {
; #pragma unroll
;                 for (int g = 3; g >= 0; --g) {
;                     if (g == fq) { AP = AW; BP = BW; }
;                     BW = Ag[g] * BW + Bg[g]; AW *= Ag[g];
;                 }
;             }
;             apre[nn][d] = AP; bpre[nn][d] = BP;
;             if (fq == 0) { wagg[((w * 2 + d) * 64 + ch) * 2 + 0] = AW; wagg[((w * 2 + d) * 64 + ch) * 2 + 1] = BW; }
	v_fma_f32 v198, -v31, v31, 1.0
	v_rcp_f32_e32 v35, v35
	v_sqrt_f32_e32 v198, v198
	v_add_f32_e32 v32, 1.0, v32
	v_rcp_f32_e32 v32, v32
	v_fmamk_f32 v33, v33, 0xbfb8aa3b, v242
	v_mul_f32_e32 v35, v35, v198
	v_exp_f32_e32 v198, v33
	v_mul_f32_e32 v32, v229, v32
	v_exp_f32_e32 v33, v32
	v_fmamk_f32 v36, v36, 0xbfb8aa3b, v243
	v_add_f32_e32 v32, 1.0, v198
	v_rcp_f32_e32 v32, v32
	v_fmamk_f32 v203, v37, 0xbfb8aa3b, v243
	v_exp_f32_e32 v200, v203
	v_exp_f32_e32 v36, v36
	v_mul_f32_e32 v32, v229, v32
	v_exp_f32_e32 v37, v32
	v_add_f32_e32 v32, 1.0, v200
	v_add_f32_e32 v36, 1.0, v36
	v_fma_f32 v198, -v33, v33, 1.0
	v_rcp_f32_e32 v200, v32
	v_fma_f32 v32, -v37, v37, 1.0
	v_rcp_f32_e32 v36, v36
	v_sqrt_f32_e32 v198, v198
	v_sqrt_f32_e32 v202, v32
	v_mul_f32_e32 v30, v30, v209
	v_mul_f32_e32 v32, v35, v207
	v_mul_f32_e32 v35, v36, v198
	v_mul_f32_e32 v36, v200, v202
	v_fma_f32 v200, 0, v34, v30
	v_lshlrev_b32_e32 v208, 16, v228
	v_mul_f32_e32 v35, v35, v206
	v_mul_f32_e32 v198, v34, v31
	v_fma_f32 v200, v31, v200, v32
	v_mul_f32_e32 v36, v36, v208
	v_mul_f32_e32 v198, v33, v198
	v_fma_f32 v200, v33, v200, v35
	v_mul_f32_e32 v198, v37, v198
	v_fma_f32 v200, v37, v200, v36
	v_mov_b32_e32 v204, v198
	v_mov_b32_e32 v202, v200
	s_nop 0
	v_permlane16_swap_b32_e32 v198, v204
	v_permlane16_swap_b32_e32 v200, v202
	v_mov_b32_e32 v205, v198
	v_mov_b32_e32 v203, v200
	s_nop 0
	v_permlane32_swap_b32_e32 v198, v205
	v_mov_b32_e32 v211, v204
	v_permlane32_swap_b32_e32 v200, v203
	v_mov_b32_e32 v212, v202
	v_permlane32_swap_b32_e32 v204, v211
	s_nop 0
	v_permlane32_swap_b32_e32 v202, v212
	v_fmac_f32_e32 v202, v200, v204
	v_mul_f32_e32 v204, v198, v204
	v_fmac_f32_e32 v203, v202, v205
	v_mul_f32_e32 v205, v204, v205
	s_and_saveexec_b64 s[28:29], s[10:11]
	v_mul_f32_e32 v213, v203, v211
	v_mul_f32_e32 v214, v205, v211
	v_add_f32_e32 v215, v213, v212
	ds_write_b64 v152, v[214:215] offset:52736
	s_or_b64 exec, exec, s[28:29]
	v_fmamk_f32 v22, v22, 0xbfb8aa3b, v244
	v_exp_f32_e32 v22, v22
	v_fmamk_f32 v23, v23, 0xbfb8aa3b, v244
	v_exp_f32_e32 v23, v23
	v_fmamk_f32 v26, v26, 0xbfb8aa3b, v245
	v_add_f32_e32 v22, 1.0, v22
	v_rcp_f32_e32 v22, v22
	v_add_f32_e32 v23, 1.0, v23
	v_exp_f32_e32 v26, v26
	v_rcp_f32_e32 v23, v23
	v_mul_f32_e32 v22, v231, v22
	v_exp_f32_e32 v22, v22
	v_fmamk_f32 v24, v24, 0xbfb8aa3b, v244
	v_fmamk_f32 v27, v27, 0xbfb8aa3b, v245
	v_add_f32_e32 v26, 1.0, v26
	v_mul_f32_e32 v23, v231, v23
	v_fma_f32 v213, -v22, v22, 1.0
	v_exp_f32_e32 v24, v24
	v_fmamk_f32 v25, v25, 0xbfb8aa3b, v244
	v_exp_f32_e32 v27, v27
	v_rcp_f32_e32 v26, v26
	v_exp_f32_e32 v23, v23
	v_sqrt_f32_e32 v213, v213
	v_exp_f32_e32 v25, v25
	v_add_f32_e32 v24, 1.0, v24
	v_add_f32_e32 v27, 1.0, v27
	v_fma_f32 v214, -v23, v23, 1.0
	v_mul_f32_e32 v26, v26, v213
	v_fmamk_f32 v28, v28, 0xbfb8aa3b, v245
	v_rcp_f32_e32 v24, v24
	v_add_f32_e32 v25, 1.0, v25
	v_rcp_f32_e32 v27, v27
	v_mul_f32_e32 v26, v26, v209
	v_sqrt_f32_e32 v209, v214
	v_exp_f32_e32 v28, v28
	v_rcp_f32_e32 v25, v25
	v_mul_f32_e32 v24, v231, v24
	v_fmamk_f32 v211, v29, 0xbfb8aa3b, v245
	v_mul_f32_e32 v209, v27, v209
	v_add_f32_e32 v27, 1.0, v28
	v_exp_f32_e32 v24, v24
	v_exp_f32_e32 v29, v211
	v_mul_f32_e32 v25, v231, v25
	v_rcp_f32_e32 v28, v27
	v_exp_f32_e32 v27, v25
	v_fma_f32 v210, -v24, v24, 1.0
	v_add_f32_e32 v25, 1.0, v29
	v_sqrt_f32_e32 v210, v210
	v_rcp_f32_e32 v29, v25
	v_fma_f32 v25, -v27, v27, 1.0
	v_sqrt_f32_e32 v211, v25
	v_mul_f32_e32 v28, v28, v210
	v_mul_f32_e32 v28, v28, v206
	v_mul_f32_e32 v206, v27, v24
	v_mul_f32_e32 v29, v29, v211
	v_mul_f32_e32 v29, v29, v208
	v_mul_f32_e32 v206, v23, v206
	v_mul_f32_e32 v212, v22, v206
	v_fma_f32 v206, 0, v27, v29
	v_mul_f32_e32 v25, v209, v207
	v_fma_f32 v206, v24, v206, v28
	v_fma_f32 v206, v23, v206, v25
	v_fma_f32 v213, v22, v206, v26
	v_mov_b32_e32 v211, v212
	v_mov_b32_e32 v207, v213
	s_nop 0
	v_permlane16_swap_b32_e32 v212, v211
	v_permlane16_swap_b32_e32 v213, v207
	v_mov_b32_e32 v206, v211
	v_mov_b32_e32 v209, v207
	v_mov_b32_e32 v210, v212
	v_permlane32_swap_b32_e32 v211, v206
	v_mov_b32_e32 v208, v213
	v_permlane32_swap_b32_e32 v207, v209
	v_permlane32_swap_b32_e32 v212, v210
	v_permlane32_swap_b32_e32 v213, v208
	v_fmac_f32_e32 v208, v209, v210
	v_mul_f32_e32 v210, v210, v206
	v_fmac_f32_e32 v207, v208, v211
	v_mul_f32_e32 v211, v210, v211
	s_and_saveexec_b64 s[28:29], s[10:11]
	v_mul_f32_e32 v214, v207, v212
	v_mul_f32_e32 v212, v211, v212
	v_add_f32_e32 v213, v214, v213
	ds_write_b64 v152, v[212:213] offset:53248
	s_or_b64 exec, exec, s[28:29]
	s_waitcnt lgkmcnt(0)
	s_barrier
; template <bool PASS_C>
; DEVI void lru_item(const P& p, int item, int next_item, uint4& u0, uint4& u1, uint4& u2, float& cpre, char* smem) {
;     ...
; #pragma unroll
;         for (int nn = 0; nn < 4; ++nn) {
;             const int ch = 16 * nn + fr;
;             float y[4];
;             {
;                 float hw = carry[ch];
; #pragma unroll
;                 for (int ww = 0; ww < 4; ++ww)
;                     if (ww < w) hw = wagg[((ww * 2 + 0) * 64 + ch) * 2] * hw + wagg[((ww * 2 + 0) * 64 + ch) * 2 + 1];
;                 float hh = apre[nn][0] * hw + bpre[nn][0];
; #pragma unroll
;                 for (int j = 0; j < 4; ++j) { hh = av[nn][0][j] * hh + bv[nn][0][j]; y[j] = hh; }
;             }
;             {
;                 float hw = carry[64 + ch];
; #pragma unroll
;     ...
;                     if (ww > w) hw = wagg[((ww * 2 + 1) * 64 + ch) * 2] * hw + wagg[((ww * 2 + 1) * 64 + ch) * 2 + 1];
;                 float hh = apre[nn][1] * hw + bpre[nn][1];
; #pragma unroll
;                 for (int j = 3; j >= 0; --j) { hh = av[nn][1][j] * hh + bv[nn][1][j]; y[j] += hh; }
;             }
; #pragma unroll
;             for (int j = 0; j < 4; ++j) ytile[(16 * w + 4 * fq + j) * 66 + ch] = y[j];
	ds_read_b32 v244, v122 offset:56832
	ds_read_b32 v245, v122 offset:57088
	ds_read_b64 v[232:233], v123 offset:52736
	ds_read_b64 v[234:235], v123 offset:53760
	ds_read_b64 v[236:237], v123 offset:54784
	ds_read_b64 v[238:239], v123 offset:56320
	ds_read_b64 v[240:241], v123 offset:55296
	ds_read_b64 v[242:243], v123 offset:54272
	ds_read_b32 v246, v122 offset:56896
	ds_read_b32 v247, v122 offset:57152
	ds_read_b64 v[218:219], v154 offset:52736
	ds_read_b64 v[220:221], v154 offset:53760
	ds_read_b64 v[222:223], v154 offset:54784
	ds_read_b64 v[224:225], v154 offset:56320
	ds_read_b64 v[226:227], v154 offset:55296
	ds_read_b64 v[228:229], v154 offset:54272
	s_waitcnt lgkmcnt(8)
	v_fma_f32 v248, v232, v244, v233
	v_cndmask_b32_e64 v212, v244, v248, s[4:5]
	v_fma_f32 v248, v234, v212, v235
	v_cndmask_b32_e64 v212, v212, v248, s[18:19]
	v_fma_f32 v248, v236, v212, v237
	v_cndmask_b32_e64 v212, v212, v248, s[20:21]
	v_fma_f32 v248, v238, v245, v239
	v_cndmask_b32_e64 v213, v245, v248, s[24:25]
	v_fma_f32 v248, v240, v213, v241
	v_cndmask_b32_e64 v213, v213, v248, s[8:9]
	v_fma_f32 v248, v242, v213, v243
	v_cndmask_b32_e64 v213, v213, v248, s[2:3]
	v_cndmask_b32_e64 v103, 1.0, v103, s[12:13]
	v_cndmask_b32_e64 v105, 0, v105, s[12:13]
	v_cndmask_b32_e64 v103, v103, v159, s[14:15]
	v_cndmask_b32_e64 v105, v105, v157, s[14:15]
	v_cndmask_b32_e64 v103, v103, v160, s[16:17]
	v_cndmask_b32_e64 v105, v105, v158, s[16:17]
	v_fmac_f32_e32 v105, v103, v212
	v_fmac_f32_e32 v87, v89, v105
	v_fmac_f32_e32 v93, v91, v87
	v_cndmask_b32_e64 v89, 1.0, v162, s[14:15]
	v_cndmask_b32_e64 v91, 0, v164, s[14:15]
	v_cndmask_b32_e64 v89, v89, v166, s[12:13]
	v_cndmask_b32_e64 v91, v91, v163, s[12:13]
	v_cndmask_b32_e64 v89, v89, v167, s[10:11]
	v_cndmask_b32_e64 v91, v91, v161, s[10:11]
	v_fmac_f32_e32 v91, v89, v213
	v_fmac_f32_e32 v77, v75, v91
	v_fmac_f32_e32 v76, v72, v77
	v_fmac_f32_e32 v73, v71, v76
	v_fmac_f32_e32 v97, v95, v93
	v_fmac_f32_e32 v74, v70, v73
	v_fmac_f32_e32 v99, v101, v97
	v_add_f32_e32 v71, v93, v73
	v_add_f32_e32 v73, v87, v74
	v_add_u32_e32 v70, 0x8c00, v153
	v_add_f32_e32 v75, v99, v77
	v_add_f32_e32 v72, v97, v76
	ds_write2_b32 v70, v73, v71 offset1:66
	ds_write2_b32 v70, v72, v75 offset0:132 offset1:198
	ds_read_b32 v244, v122 offset:56960
	ds_read_b32 v245, v122 offset:57216
	ds_read_b64 v[232:233], v155 offset:52736
	ds_read_b64 v[234:235], v155 offset:53760
	ds_read_b64 v[236:237], v155 offset:54784
	ds_read_b64 v[238:239], v155 offset:56320
	ds_read_b64 v[240:241], v155 offset:55296
	ds_read_b64 v[242:243], v155 offset:54272
	s_waitcnt lgkmcnt(10)
	v_fma_f32 v248, v218, v246, v219
	v_cndmask_b32_e64 v71, v246, v248, s[4:5]
	v_fma_f32 v248, v220, v71, v221
	v_cndmask_b32_e64 v71, v71, v248, s[18:19]
	v_fma_f32 v248, v222, v71, v223
	v_cndmask_b32_e64 v71, v71, v248, s[20:21]
	v_fma_f32 v248, v224, v247, v225
	v_cndmask_b32_e64 v72, v247, v248, s[24:25]
	v_fma_f32 v248, v226, v72, v227
	v_cndmask_b32_e64 v72, v72, v248, s[8:9]
	v_fma_f32 v248, v228, v72, v229
	v_cndmask_b32_e64 v72, v72, v248, s[2:3]
	v_cndmask_b32_e64 v73, 1.0, v165, s[12:13]
	v_cndmask_b32_e64 v74, 0, v168, s[12:13]
	v_cndmask_b32_e64 v73, v73, v171, s[14:15]
	v_cndmask_b32_e64 v74, v74, v169, s[14:15]
	v_cndmask_b32_e64 v73, v73, v173, s[16:17]
	v_cndmask_b32_e64 v74, v74, v170, s[16:17]
	v_fmac_f32_e32 v74, v73, v71
	v_fmac_f32_e32 v62, v66, v74
	v_fmac_f32_e32 v64, v63, v62
	v_fmac_f32_e32 v67, v65, v64
	v_cndmask_b32_e64 v63, 1.0, v183, s[14:15]
	v_cndmask_b32_e64 v65, 0, v185, s[14:15]
	v_cndmask_b32_e64 v63, v63, v187, s[12:13]
	v_cndmask_b32_e64 v65, v65, v184, s[12:13]
	v_cndmask_b32_e64 v63, v63, v188, s[10:11]
	v_cndmask_b32_e64 v65, v65, v177, s[10:11]
	v_fmac_f32_e32 v65, v63, v72
	v_fmac_f32_e32 v61, v59, v65
	v_fmac_f32_e32 v60, v56, v61
	v_fmac_f32_e32 v57, v55, v60
	v_fmac_f32_e32 v58, v54, v57
	v_fmac_f32_e32 v68, v69, v67
	v_add_f32_e32 v55, v64, v57
	v_add_f32_e32 v54, v62, v58
	v_add_f32_e32 v59, v68, v61
	v_add_f32_e32 v56, v67, v60
	ds_write2_b32 v70, v54, v55 offset0:16 offset1:82
	ds_write2_b32 v70, v56, v59 offset0:148 offset1:214
	ds_read_b32 v246, v122 offset:57024
	ds_read_b32 v247, v122 offset:57280
	ds_read_b64 v[218:219], v156 offset:52736
	ds_read_b64 v[220:221], v156 offset:53760
	ds_read_b64 v[222:223], v156 offset:54784
	ds_read_b64 v[224:225], v156 offset:56320
	ds_read_b64 v[226:227], v156 offset:55296
	ds_read_b64 v[228:229], v156 offset:54272
	s_waitcnt lgkmcnt(10)
	v_fma_f32 v248, v232, v244, v233
	v_cndmask_b32_e64 v54, v244, v248, s[4:5]
	v_fma_f32 v248, v234, v54, v235
	v_cndmask_b32_e64 v54, v54, v248, s[18:19]
	v_fma_f32 v248, v236, v54, v237
	v_cndmask_b32_e64 v54, v54, v248, s[20:21]
	v_fma_f32 v248, v238, v245, v239
	v_cndmask_b32_e64 v55, v245, v248, s[24:25]
	v_fma_f32 v248, v240, v55, v241
	v_cndmask_b32_e64 v55, v55, v248, s[8:9]
	v_fma_f32 v248, v242, v55, v243
	v_cndmask_b32_e64 v55, v55, v248, s[2:3]
	v_cndmask_b32_e64 v56, 1.0, v186, s[12:13]
	v_cndmask_b32_e64 v57, 0, v189, s[12:13]
	v_cndmask_b32_e64 v56, v56, v192, s[14:15]
	v_cndmask_b32_e64 v57, v57, v190, s[14:15]
	v_cndmask_b32_e64 v56, v56, v193, s[16:17]
	v_cndmask_b32_e64 v57, v57, v191, s[16:17]
	v_fmac_f32_e32 v57, v56, v54
	v_fmac_f32_e32 v46, v50, v57
	v_fmac_f32_e32 v48, v47, v46
	v_fmac_f32_e32 v51, v49, v48
	v_cndmask_b32_e64 v47, 1.0, v195, s[14:15]
	v_cndmask_b32_e64 v49, 0, v197, s[14:15]
	v_cndmask_b32_e64 v47, v47, v199, s[12:13]
	v_cndmask_b32_e64 v49, v49, v196, s[12:13]
	v_cndmask_b32_e64 v47, v47, v201, s[10:11]
	v_cndmask_b32_e64 v49, v49, v194, s[10:11]
	v_fmac_f32_e32 v49, v47, v55
	v_fmac_f32_e32 v45, v43, v49
	v_fmac_f32_e32 v44, v40, v45
	v_fmac_f32_e32 v41, v39, v44
	v_fmac_f32_e32 v42, v38, v41
	v_fmac_f32_e32 v52, v53, v51
	v_add_f32_e32 v39, v48, v41
	v_add_f32_e32 v38, v46, v42
	v_add_f32_e32 v43, v52, v45
	v_add_f32_e32 v40, v51, v44
	ds_write2_b32 v70, v38, v39 offset0:32 offset1:98
	ds_write2_b32 v70, v40, v43 offset0:164 offset1:230
	s_waitcnt lgkmcnt(2)
	v_fma_f32 v248, v218, v246, v219
	v_cndmask_b32_e64 v38, v246, v248, s[4:5]
	v_fma_f32 v248, v220, v38, v221
	v_cndmask_b32_e64 v38, v38, v248, s[18:19]
	v_fma_f32 v248, v222, v38, v223
	v_cndmask_b32_e64 v38, v38, v248, s[20:21]
	v_fma_f32 v248, v224, v247, v225
	v_cndmask_b32_e64 v39, v247, v248, s[24:25]
	v_fma_f32 v248, v226, v39, v227
	v_cndmask_b32_e64 v39, v39, v248, s[8:9]
	v_fma_f32 v248, v228, v39, v229
	v_cndmask_b32_e64 v39, v39, v248, s[2:3]
	s_branch .LBB0_720
